# accumulator zero-init moved up into the prologue load shadow (6 GEMM instances), on top of v19
# speedup vs baseline: 1.0071x; 1.0008x over previous
; DI int get_tid(int wv) { int l; asm volatile("v_mbcnt_lo_u32_b32 %0, -1, 0\n\tv_mbcnt_hi_u32_b32 %0, -1, %0" : "=v"(l)); return wv * 64 + l; }
; DI int wave_of(int tid) { return __builtin_amdgcn_readfirstlane(tid >> 6); }
; #define STAGE_A(P, br, kt) do { const char* _g = (const char*)(A + (long)(br) * lda + (long)(kt) * BK); \
;     __builtin_amdgcn_global_load_lds((const unsigned*)(_g + (size_t)offA0), (unsigned*)((char*)(P) + sb0), 16, 0, 0); \
;     __builtin_amdgcn_global_load_lds((const unsigned*)(_g + (size_t)lda * 128 + (size_t)offA0), (unsigned*)((char*)(P) + sb1), 16, 0, 0); } while (0)
; #define STAGE_B(P, br, kt) do { const char* _g = (const char*)(B + (long)(br) * ldb + (long)(kt) * BK); \
;     __builtin_amdgcn_global_load_lds((const unsigned*)(_g + (size_t)offB0), (unsigned*)((char*)(P) + sb0), 16, 0, 0); \
;     __builtin_amdgcn_global_load_lds((const unsigned*)(_g + (size_t)ldb * 128 + (size_t)offB0), (unsigned*)((char*)(P) + sb1), 16, 0, 0); } while (0)
; #define BAR __builtin_amdgcn_s_barrier()
; DI void gemm_core(WVP char* smem, const u16* __restrict__ A, int lda, int ar0, int ar1,
;                   const u16* __restrict__ B, int ldb, int bc0, int K, AccT& acc) {
;     ...
;   const int tid = get_tid(WV);
;   const int wid = wave_of(tid), lane = tid & 63, wr = wid >> 2, wc = wid & 3, fr = lane & 15, fq = lane >> 4;
;   const int sb0 = tid * 16, sb1 = sb0 + 8192;
;   int R0, C0; stage_rc(sb0, R0, C0);
;   const unsigned offA0 = (unsigned)(R0 * lda + C0) * 2u, offB0 = (unsigned)(R0 * ldb + C0) * 2u;
;   const int ac0 = ar0, ac1 = ar1, bb0 = bc0, bb1 = bc0 + HALF;
;   bf16x8 At[4][2], B0[2][2], B1[2][2];
;   const int nt = K / BK;
;   __syncthreads();
;   STAGE_B(SB(0, 0), bb0, 0); STAGE_A(SA(0, 0), ac0, 0);
;   STAGE_B(SB(0, 1), bb1, 0); STAGE_A(SA(0, 1), ac1, 0);
;   if (wr == 1) BAR;
.LBB0_91:
	s_add_i32 s0, s1, s8
	s_ashr_i32 s1, s0, 31
	s_lshr_b32 s1, s1, 23
	s_add_i32 s1, s0, s1
	s_ashr_i32 s8, s1, 9
	s_and_b32 s1, s1, 0xfe00
	s_sub_i32 s0, s0, s1
	s_sext_i32_i16 s1, s0
	s_bfe_u32 s1, s1, 0x2001d
	v_mbcnt_lo_u32_b32 v6, -1, 0
	v_mbcnt_hi_u32_b32 v6, -1, v6
	s_add_i32 s1, s0, s1
	v_add_u32_e32 v0, s3, v6
	v_ashrrev_i32_e32 v2, 31, v0
	s_lshl_b32 s29, s8, 2
	s_sext_i32_i16 s8, s1
	s_and_b32 s1, s1, 0xfffc
	v_lshrrev_b32_e32 v2, 26, v2
	s_sub_i32 s0, s0, s1
	v_readfirstlane_b32 s1, v0
	v_lshlrev_b32_e32 v11, 4, v0
	v_add_u32_e32 v2, v0, v2
	v_bfe_i32 v0, v0, 27, 1
	v_lshrrev_b32_e32 v0, 22, v0
	v_add_u32_e32 v0, v11, v0
	v_and_b32_e32 v0, 0xfffffc00, v0
	v_sub_u32_e32 v0, v11, v0
	v_ashrrev_i32_e32 v7, 6, v2
	v_lshrrev_b32_e32 v2, 4, v0
	v_bitop3_b32 v0, v2, v0, 32 bitop3:0x6c
	v_ashrrev_i32_e32 v3, 31, v0
	v_lshrrev_b32_e32 v3, 26, v3
	v_add_u32_e32 v3, v0, v3
	v_lshlrev_b32_e32 v2, 3, v7
	v_ashrrev_i32_e32 v9, 6, v3
	v_and_b32_e32 v3, 0xc0, v3
	v_and_b32_e32 v2, 0xfffff0, v2
	v_sub_u32_e32 v0, v0, v3
	s_sext_i32_i16 s0, s0
	s_ashr_i32 s30, s8, 2
	v_add_u32_e32 v2, v9, v2
	v_ashrrev_i16_sdwa v0, v254, sext(v0) dst_sel:DWORD dst_unused:UNUSED_PAD src0_sel:DWORD src1_sel:BYTE_0
	s_movk_i32 s8, 0xb00
	s_add_i32 s29, s29, s0
	v_bfe_i32 v10, v0, 0, 16
	v_mul_lo_u32 v0, v2, s8
	s_mul_i32 s8, s30, 0xb0000
	s_lshl_b32 s14, s29, 8
	s_ashr_i32 s9, s8, 31
	s_or_b32 s18, s14, 0x80
	s_ashr_i32 s0, s1, 8
	s_lshl_b64 s[8:9], s[8:9], 1
	s_add_u32 s8, s54, s8
	v_lshlrev_b32_e32 v4, 5, v7
	s_addc_u32 s9, s55, s9
	s_add_i32 s19, 0, 0x10000
	v_add_u32_e32 v14, 0x2000, v11
	v_and_b32_e32 v8, 32, v4
	v_add_u32_e32 v134, s19, v11
	v_or_b32_e32 v0, v0, v8
	v_readfirstlane_b32 s15, v134
	v_add_u32_e32 v12, s19, v14
	v_add_lshl_u32 v0, v0, v10, 1
	s_mov_b32 m0, s15
	v_readfirstlane_b32 s15, v12
	s_barrier
	v_lshl_add_u64 v[2:3], s[8:9], 0, v[0:1]
	global_load_lds_dwordx4 v0, s[8:9]
	s_mov_b64 s[36:37], 0x58000
	s_mov_b32 m0, s15
	s_ashr_i32 s15, s14, 31
	s_mul_i32 s16, s29, 0x160000
	v_readlane_b32 s23, v255, 40
	v_add_u32_e32 v135, 0, v11
	v_lshl_add_u64 v[4:5], v[2:3], 0, s[36:37]
	s_mul_hi_i32 s17, s14, 0x1600
	s_add_u32 s20, s23, s16
	v_readlane_b32 s28, v255, 41
	v_readfirstlane_b32 s22, v135
	global_load_lds_dwordx4 v[4:5], off
	s_addc_u32 s21, s28, s17
	s_mov_b32 m0, s22
	v_add_u32_e32 v136, 0x2000, v135
	v_lshl_add_u64 v[4:5], s[20:21], 0, v[0:1]
	global_load_lds_dwordx4 v0, s[20:21]
	v_readfirstlane_b32 s20, v136
	v_lshl_add_u64 v[12:13], v[4:5], 0, s[36:37]
	s_mov_b32 m0, s20
	s_mov_b64 s[20:21], 0xb0000
	v_add_u32_e32 v138, s60, v11
	global_load_lds_dwordx4 v[12:13], off
	v_lshl_add_u64 v[12:13], v[2:3], 0, s[20:21]
	v_readfirstlane_b32 s20, v138
	s_mov_b32 m0, s20
	s_mov_b64 s[20:21], 0x108000
	v_add_u32_e32 v14, s60, v14
	global_load_lds_dwordx4 v[12:13], off
	v_lshl_add_u64 v[12:13], v[2:3], 0, s[20:21]
	v_readfirstlane_b32 s20, v14
	s_mul_hi_i32 s21, s18, 0x1600
	s_mulk_i32 s18, 0x1600
	s_mov_b32 m0, s20
	s_add_u32 s20, s23, s18
	v_add_u32_e32 v139, 0x4000, v135
	s_addc_u32 s21, s28, s21
	v_readfirstlane_b32 s18, v139
	v_add_u32_e32 v140, 0x6000, v135
	global_load_lds_dwordx4 v[12:13], off
	v_lshl_add_u64 v[130:131], s[20:21], 0, v[0:1]
	s_mov_b32 m0, s18
	v_readfirstlane_b32 s18, v140
	global_load_lds_dwordx4 v0, s[20:21]
	v_lshl_add_u64 v[12:13], v[130:131], 0, s[36:37]
	s_mov_b32 m0, s18
	s_cmp_lg_u32 s0, 1
	global_load_lds_dwordx4 v[12:13], off
	v_mov_b32_e32 v16, 0
	v_mov_b32_e32 v17, 0
	v_mov_b32_e32 v18, 0
	v_mov_b32_e32 v19, 0
	v_mov_b32_e32 v20, 0
	v_mov_b32_e32 v21, 0
	v_mov_b32_e32 v22, 0
	v_mov_b32_e32 v23, 0
	v_mov_b32_e32 v24, 0
	v_mov_b32_e32 v25, 0
	v_mov_b32_e32 v26, 0
	v_mov_b32_e32 v27, 0
	v_mov_b32_e32 v28, 0
	v_mov_b32_e32 v29, 0
	v_mov_b32_e32 v30, 0
	v_mov_b32_e32 v31, 0
	v_mov_b32_e32 v32, 0
	v_mov_b32_e32 v33, 0
	v_mov_b32_e32 v34, 0
	v_mov_b32_e32 v35, 0
	v_mov_b32_e32 v36, 0
	v_mov_b32_e32 v37, 0
	v_mov_b32_e32 v38, 0
	v_mov_b32_e32 v39, 0
	v_mov_b32_e32 v40, 0
	v_mov_b32_e32 v41, 0
	v_mov_b32_e32 v42, 0
	v_mov_b32_e32 v43, 0
	v_mov_b32_e32 v44, 0
	v_mov_b32_e32 v45, 0
	v_mov_b32_e32 v46, 0
	v_mov_b32_e32 v47, 0
	v_mov_b32_e32 v48, 0
	v_mov_b32_e32 v49, 0
	v_mov_b32_e32 v50, 0
	v_mov_b32_e32 v51, 0
	v_mov_b32_e32 v52, 0
	v_mov_b32_e32 v53, 0
	v_mov_b32_e32 v54, 0
	v_mov_b32_e32 v55, 0
	v_mov_b32_e32 v56, 0
	v_mov_b32_e32 v57, 0
	v_mov_b32_e32 v58, 0
	v_mov_b32_e32 v59, 0
	v_mov_b32_e32 v60, 0
	v_mov_b32_e32 v61, 0
	v_mov_b32_e32 v62, 0
	v_mov_b32_e32 v63, 0
	v_mov_b32_e32 v64, 0
	v_mov_b32_e32 v65, 0
	v_mov_b32_e32 v66, 0
	v_mov_b32_e32 v67, 0
	v_mov_b32_e32 v68, 0
	v_mov_b32_e32 v69, 0
	v_mov_b32_e32 v70, 0
	v_mov_b32_e32 v71, 0
	v_mov_b32_e32 v72, 0
	v_mov_b32_e32 v73, 0
	v_mov_b32_e32 v74, 0
	v_mov_b32_e32 v75, 0
	v_mov_b32_e32 v76, 0
	v_mov_b32_e32 v77, 0
	v_mov_b32_e32 v78, 0
	v_mov_b32_e32 v79, 0
	v_mov_b32_e32 v80, 0
	v_mov_b32_e32 v81, 0
	v_mov_b32_e32 v82, 0
	v_mov_b32_e32 v83, 0
	v_mov_b32_e32 v84, 0
	v_mov_b32_e32 v85, 0
	v_mov_b32_e32 v86, 0
	v_mov_b32_e32 v87, 0
	v_mov_b32_e32 v88, 0
	v_mov_b32_e32 v89, 0
	v_mov_b32_e32 v90, 0
	v_mov_b32_e32 v91, 0
	v_mov_b32_e32 v92, 0
	v_mov_b32_e32 v93, 0
	v_mov_b32_e32 v94, 0
	v_mov_b32_e32 v95, 0
	v_mov_b32_e32 v96, 0
	v_mov_b32_e32 v97, 0
	v_mov_b32_e32 v98, 0
	v_mov_b32_e32 v99, 0
	v_mov_b32_e32 v100, 0
	v_mov_b32_e32 v101, 0
	v_mov_b32_e32 v102, 0
	v_mov_b32_e32 v103, 0
	v_mov_b32_e32 v104, 0
	v_mov_b32_e32 v105, 0
	v_mov_b32_e32 v106, 0
	v_mov_b32_e32 v107, 0
	v_mov_b32_e32 v108, 0
	v_mov_b32_e32 v109, 0
	v_mov_b32_e32 v110, 0
	v_mov_b32_e32 v111, 0
	v_mov_b32_e32 v112, 0
	v_mov_b32_e32 v113, 0
	v_mov_b32_e32 v114, 0
	v_mov_b32_e32 v115, 0
	v_mov_b32_e32 v116, 0
	v_mov_b32_e32 v117, 0
	v_mov_b32_e32 v118, 0
	v_mov_b32_e32 v119, 0
	v_mov_b32_e32 v120, 0
	v_mov_b32_e32 v121, 0
	v_mov_b32_e32 v122, 0
	v_mov_b32_e32 v123, 0
	v_mov_b32_e32 v124, 0
	v_mov_b32_e32 v125, 0
	v_mov_b32_e32 v126, 0
	v_mov_b32_e32 v127, 0
	v_mov_b32_e32 v128, 0
	v_mov_b32_e32 v129, 0
	s_cbranch_scc1 .LBB0_93
	s_barrier
; DI int wave_of(int tid) { return __builtin_amdgcn_readfirstlane(tid >> 6); }
; #define STAGE_A(P, br, kt) do { const char* _g = (const char*)(A + (long)(br) * lda + (long)(kt) * BK); \
;     __builtin_amdgcn_global_load_lds((const unsigned*)(_g + (size_t)offA0), (unsigned*)((char*)(P) + sb0), 16, 0, 0); \
;     __builtin_amdgcn_global_load_lds((const unsigned*)(_g + (size_t)lda * 128 + (size_t)offA0), (unsigned*)((char*)(P) + sb1), 16, 0, 0); } while (0)
; #define STAGE_B(P, br, kt) do { const char* _g = (const char*)(B + (long)(br) * ldb + (long)(kt) * BK); \
;     __builtin_amdgcn_global_load_lds((const unsigned*)(_g + (size_t)offB0), (unsigned*)((char*)(P) + sb0), 16, 0, 0); \
;     __builtin_amdgcn_global_load_lds((const unsigned*)(_g + (size_t)ldb * 128 + (size_t)offB0), (unsigned*)((char*)(P) + sb1), 16, 0, 0); } while (0)
; #define WAIT_V(n) asm volatile("s_waitcnt vmcnt(" #n ")" ::: "memory")
; #define BAR __builtin_amdgcn_s_barrier()
; DI void gemm_core(WVP char* smem, const u16* __restrict__ A, int lda, int ar0, int ar1,
;                   const u16* __restrict__ B, int ldb, int bc0, int K, AccT& acc) {
;     ...
;   const int wid = wave_of(tid), lane = tid & 63, wr = wid >> 2, wc = wid & 3, fr = lane & 15, fq = lane >> 4;
;   const int sb0 = tid * 16, sb1 = sb0 + 8192;
;   int R0, C0; stage_rc(sb0, R0, C0);
;   const unsigned offA0 = (unsigned)(R0 * lda + C0) * 2u, offB0 = (unsigned)(R0 * ldb + C0) * 2u;
;   const int ac0 = ar0, ac1 = ar1, bb0 = bc0, bb1 = bc0 + HALF;
;   bf16x8 At[4][2], B0[2][2], B1[2][2];
;   const int nt = K / BK;
;   __syncthreads();
;   STAGE_B(SB(0, 0), bb0, 0); STAGE_A(SA(0, 0), ac0, 0);
;   STAGE_B(SB(0, 1), bb1, 0); STAGE_A(SA(0, 1), ac1, 0);
;   if (wr == 1) BAR;
;   WAIT_V(4); BAR;
;   STAGE_B(SB(1, 0), bb0, 1); STAGE_A(SA(1, 0), ac0, 1); STAGE_B(SB(1, 1), bb1, 1);
;   WAIT_V(6); BAR;
.LBB0_93:
	v_add_u32_e32 v141, s61, v11
	s_ashr_i32 s18, s1, 6
	v_readfirstlane_b32 s1, v141
	v_add_u32_e32 v142, 0x2000, v141
	v_lshl_add_u64 v[12:13], v[2:3], 0, s[64:65]
	s_mov_b32 m0, s1
	s_mov_b64 s[20:21], 0x58080
	v_readfirstlane_b32 s1, v142
	v_add_u32_e32 v143, 0x8000, v135
	s_waitcnt vmcnt(4)
	s_barrier
	global_load_lds_dwordx4 v[12:13], off
	v_lshl_add_u64 v[12:13], v[2:3], 0, s[20:21]
	s_mov_b32 m0, s1
	v_readfirstlane_b32 s1, v143
	v_add_u32_e32 v144, 0xa000, v135
	global_load_lds_dwordx4 v[12:13], off
	v_lshl_add_u64 v[12:13], v[4:5], 0, s[64:65]
	s_mov_b32 m0, s1
	v_readfirstlane_b32 s1, v144
	v_add_u32_e32 v145, s84, v11
	global_load_lds_dwordx4 v[12:13], off
	v_lshl_add_u64 v[4:5], v[4:5], 0, s[20:21]
	s_mov_b32 m0, s1
	s_mov_b64 s[20:21], 0xb0080
	v_readfirstlane_b32 s1, v145
	v_add_u32_e32 v147, 0x2000, v145
	global_load_lds_dwordx4 v[4:5], off
	v_lshl_add_u64 v[4:5], v[2:3], 0, s[20:21]
	s_mov_b32 m0, s1
	s_mov_b64 s[20:21], 0x108080
	v_readfirstlane_b32 s1, v147
	global_load_lds_dwordx4 v[4:5], off
	v_lshl_add_u64 v[2:3], v[2:3], 0, s[20:21]
	s_mov_b32 m0, s1
	v_and_b32_e32 v0, 15, v6
	global_load_lds_dwordx4 v[2:3], off
	v_lshlrev_b32_e32 v2, 2, v6
	v_and_b32_e32 v14, 48, v6
	v_lshlrev_b32_e32 v0, 6, v0
	v_and_b32_e32 v2, 32, v2
	v_bitop3_b32 v0, v0, v2, v14 bitop3:0x36
	v_add_u32_e32 v4, s19, v0
	v_add_u32_e32 v5, s60, v0
	v_add_u32_e32 v11, s61, v0
	v_add_u32_e32 v12, s84, v0
	v_add_u32_e32 v13, 0, v0
	v_lshlrev_b32_e32 v0, 6, v6
	v_and_or_b32 v0, v0, s74, v14
	s_movk_i32 s20, 0xb00
	s_lshl_b32 s1, s18, 12
	s_lshl_b32 s23, s0, 13
	v_xad_u32 v148, v0, v2, 0
	v_lshrrev_b32_e32 v2, 1, v7
	v_mul_lo_u32 v0, v9, s20
	s_mov_b32 s20, 0xb000
	s_waitcnt vmcnt(6)
	s_and_b32 s22, s1, 0x3000
	s_or_b32 s0, s23, 0x800
	s_or_b32 s1, s23, 0x1000
	s_or_b32 s19, s23, 0x1800
	v_mad_u64_u32 v[2:3], s[20:21], v2, s20, v[0:1]
	v_or_b32_e32 v0, v2, v8
	s_add_u32 s16, s54, s16
	v_mov_b32_e32 v2, 0
	v_add_lshl_u32 v0, v0, v10, 1
	s_addc_u32 s17, s55, s17
	s_mov_b32 s20, -2
	v_add_u32_e32 v149, s22, v4
	v_add_u32_e32 v132, s23, v13
	v_add_u32_e32 v146, s22, v5
	v_add_u32_e32 v137, s22, v11
	v_add_u32_e32 v133, s22, v12
	v_mov_b32_e32 v3, v2
	v_mov_b32_e32 v4, v2
	v_mov_b32_e32 v5, v2
	v_mov_b32_e32 v6, v2
	v_mov_b32_e32 v7, v2
	v_mov_b32_e32 v8, v2
	v_mov_b32_e32 v9, v2
	v_mov_b32_e32 v10, v2
	v_mov_b32_e32 v11, v2
	v_mov_b32_e32 v12, v2
	v_mov_b32_e32 v13, v2
	v_mov_b32_e32 v14, v2
	v_mov_b32_e32 v15, v2
	s_barrier

; DI int get_tid(int wv) { int l; asm volatile("v_mbcnt_lo_u32_b32 %0, -1, 0\n\tv_mbcnt_hi_u32_b32 %0, -1, %0" : "=v"(l)); return wv * 64 + l; }
; DI int wave_of(int tid) { return __builtin_amdgcn_readfirstlane(tid >> 6); }
; #define STAGE_A(P, br, kt) do { const char* _g = (const char*)(A + (long)(br) * lda + (long)(kt) * BK); \
;     __builtin_amdgcn_global_load_lds((const unsigned*)(_g + (size_t)offA0), (unsigned*)((char*)(P) + sb0), 16, 0, 0); \
;     __builtin_amdgcn_global_load_lds((const unsigned*)(_g + (size_t)lda * 128 + (size_t)offA0), (unsigned*)((char*)(P) + sb1), 16, 0, 0); } while (0)
; #define STAGE_B(P, br, kt) do { const char* _g = (const char*)(B + (long)(br) * ldb + (long)(kt) * BK); \
;     __builtin_amdgcn_global_load_lds((const unsigned*)(_g + (size_t)offB0), (unsigned*)((char*)(P) + sb0), 16, 0, 0); \
;     __builtin_amdgcn_global_load_lds((const unsigned*)(_g + (size_t)ldb * 128 + (size_t)offB0), (unsigned*)((char*)(P) + sb1), 16, 0, 0); } while (0)
; #define BAR __builtin_amdgcn_s_barrier()
; DI void gemm_core(WVP char* smem, const u16* __restrict__ A, int lda, int ar0, int ar1,
;                   const u16* __restrict__ B, int ldb, int bc0, int K, AccT& acc) {
;     ...
;   const int tid = get_tid(WV);
;   const int wid = wave_of(tid), lane = tid & 63, wr = wid >> 2, wc = wid & 3, fr = lane & 15, fq = lane >> 4;
;   const int sb0 = tid * 16, sb1 = sb0 + 8192;
;   int R0, C0; stage_rc(sb0, R0, C0);
;   const unsigned offA0 = (unsigned)(R0 * lda + C0) * 2u, offB0 = (unsigned)(R0 * ldb + C0) * 2u;
;   const int ac0 = ar0, ac1 = ar1, bb0 = bc0, bb1 = bc0 + HALF;
;   bf16x8 At[4][2], B0[2][2], B1[2][2];
;   const int nt = K / BK;
;   __syncthreads();
;   STAGE_B(SB(0, 0), bb0, 0); STAGE_A(SA(0, 0), ac0, 0);
;   STAGE_B(SB(0, 1), bb1, 0); STAGE_A(SA(0, 1), ac1, 0);
;   if (wr == 1) BAR;
.LBB0_165:
	s_cmpk_gt_i32 s4, 0xaff
	s_cbranch_scc1 .LBB0_172
	s_ashr_i32 s0, s4, 31
	s_lshr_b32 s0, s0, 29
	s_add_i32 s0, s4, s0
	s_ashr_i32 s1, s0, 3
	s_and_b32 s0, s0, -8
	s_sub_i32 s0, s4, s0
	s_cmp_lt_i32 s0, 0
	s_movk_i32 s5, 0x161
	s_cselect_b32 s5, s5, 0x160
	s_mul_i32 s14, s0, s5
	s_add_i32 s14, s14, s1
	s_ashr_i32 s0, s14, 31
	s_lshr_b32 s0, s0, 23
	s_add_i32 s0, s14, s0
	s_ashr_i32 s15, s0, 9
	s_lshl_b32 s5, s15, 2
	s_sub_i32 s1, 22, s5
	s_min_u32 s8, s1, 4
	s_and_b32 s16, s0, 0xfffffe00
	s_sub_i32 s9, s14, s16
	v_cvt_f32_ubyte0_e32 v2, s8
	v_cvt_f32_i32_e32 v0, s9
	v_rcp_iflag_f32_e32 v3, v2
	s_ashr_i32 s0, s9, 30
	s_or_b32 s10, s0, 1
	v_mbcnt_lo_u32_b32 v9, -1, 0
	v_mbcnt_hi_u32_b32 v9, -1, v9
	v_mul_f32_e32 v3, v0, v3
	v_trunc_f32_e32 v3, v3
	v_fma_f32 v0, -v3, v2, v0
	v_cvt_i32_f32_e32 v3, v3
	v_cmp_ge_f32_e64 s[0:1], |v0|, v2
	s_and_b64 s[0:1], s[0:1], exec
	s_cselect_b32 s0, s10, 0
	v_readfirstlane_b32 s1, v3
	s_add_i32 s17, s1, s0
	s_sext_i32_i16 s0, s17
	s_mul_i32 s17, s17, s8
	v_add_u32_e32 v0, s3, v9
	s_sub_i32 s1, s9, s17
	v_ashrrev_i32_e32 v2, 31, v0
	s_sext_i32_i16 s1, s1
	v_lshrrev_b32_e32 v2, 26, v2
	s_add_i32 s5, s5, s1
	v_readfirstlane_b32 s1, v0
	v_lshlrev_b32_e32 v12, 4, v0
	v_add_u32_e32 v2, v0, v2
	v_bfe_i32 v0, v0, 27, 1
	v_lshrrev_b32_e32 v0, 22, v0
	v_add_u32_e32 v0, v12, v0
	v_and_b32_e32 v0, 0xfffffc00, v0
	v_sub_u32_e32 v0, v12, v0
	v_ashrrev_i32_e32 v8, 6, v2
	v_lshrrev_b32_e32 v2, 4, v0
	v_bitop3_b32 v0, v2, v0, 32 bitop3:0x6c
	v_ashrrev_i32_e32 v3, 31, v0
	s_lshl_b32 s8, s0, 8
	v_lshrrev_b32_e32 v3, 26, v3
	v_add_u32_e32 v3, v0, v3
	s_ashr_i32 s9, s8, 31
	s_lshl_b32 s10, s5, 7
	s_ashr_i32 s0, s1, 8
	v_ashrrev_i32_e32 v10, 6, v3
	v_and_b32_e32 v3, 0xc0, v3
	s_or_b32 s18, s8, 0x80
	s_lshl_b64 s[12:13], s[8:9], 11
	v_readlane_b32 s22, v255, 29
	v_sub_u32_e32 v0, v0, v3
	v_readlane_b32 s23, v255, 30
	s_add_u32 s20, s22, s12
	v_lshlrev_b32_e32 v2, 3, v8
	v_lshlrev_b32_e32 v4, 5, v8
	v_ashrrev_i16_sdwa v0, v254, sext(v0) dst_sel:DWORD dst_unused:UNUSED_PAD src0_sel:DWORD src1_sel:BYTE_0
	s_addc_u32 s21, s23, s13
	s_add_i32 s9, 0, 0x10000
	v_add_u32_e32 v13, 0x2000, v12
	v_and_b32_e32 v2, 0x1ffff0, v2
	v_and_b32_e32 v4, 32, v4
	v_bfe_i32 v11, v0, 0, 16
	v_add_u32_e32 v133, s9, v12
	v_add_u32_e32 v0, v4, v11
	v_add_lshl_u32 v2, v10, v2, 11
	v_readfirstlane_b32 s5, v133
	v_add_u32_e32 v6, s9, v13
	v_lshl_add_u32 v0, v0, 1, v2
	s_mov_b32 m0, s5
	v_readfirstlane_b32 s5, v6
	s_ashr_i32 s11, s10, 31
	s_barrier
	v_lshl_add_u64 v[2:3], s[20:21], 0, v[0:1]
	global_load_lds_dwordx4 v0, s[20:21]
	s_mov_b32 m0, s5
	s_lshl_b64 s[20:21], s[10:11], 11
	v_readlane_b32 s5, v255, 38
	s_add_u32 s20, s5, s20
	v_readlane_b32 s5, v255, 39
	v_add_u32_e32 v135, 0, v12
	v_lshl_add_u64 v[4:5], v[2:3], 0, s[76:77]
	s_addc_u32 s21, s5, s21
	v_readfirstlane_b32 s5, v135
	v_add_u32_e32 v136, 0x2000, v135
	s_ashr_i32 s19, s18, 31
	global_load_lds_dwordx4 v[4:5], off
	v_lshl_add_u64 v[4:5], s[20:21], 0, v[0:1]
	s_mov_b32 m0, s5
	v_readfirstlane_b32 s5, v136
	s_lshl_b64 s[18:19], s[18:19], 11
	v_add_u32_e32 v138, s60, v12
	global_load_lds_dwordx4 v0, s[20:21]
	v_lshl_add_u64 v[6:7], v[4:5], 0, s[76:77]
	s_mov_b32 m0, s5
	s_add_u32 s18, s22, s18
	v_readfirstlane_b32 s5, v138
	global_load_lds_dwordx4 v[6:7], off
	s_addc_u32 s19, s23, s19
	s_mov_b32 m0, s5
	v_add_u32_e32 v13, s60, v13
	v_lshl_add_u64 v[6:7], s[18:19], 0, v[0:1]
	global_load_lds_dwordx4 v0, s[18:19]
	v_readfirstlane_b32 s5, v13
	s_add_u32 s18, s20, 0x580000
	v_add_u32_e32 v139, 0x4000, v135
	v_lshl_add_u64 v[14:15], v[6:7], 0, s[76:77]
	s_mov_b32 m0, s5
	s_addc_u32 s19, s21, 0
	v_readfirstlane_b32 s5, v139
	v_add_u32_e32 v140, 0x6000, v135
	global_load_lds_dwordx4 v[14:15], off
	v_lshl_add_u64 v[130:131], s[18:19], 0, v[0:1]
	s_mov_b32 m0, s5
	v_readfirstlane_b32 s5, v140
	global_load_lds_dwordx4 v0, s[18:19]
	v_lshl_add_u64 v[14:15], v[130:131], 0, s[76:77]
	s_mov_b32 m0, s5
	s_cmp_lg_u32 s0, 1
	global_load_lds_dwordx4 v[14:15], off
	v_mov_b32_e32 v16, 0
	v_mov_b32_e32 v17, 0
	v_mov_b32_e32 v18, 0
	v_mov_b32_e32 v19, 0
	v_mov_b32_e32 v20, 0
	v_mov_b32_e32 v21, 0
	v_mov_b32_e32 v22, 0
	v_mov_b32_e32 v23, 0
	v_mov_b32_e32 v24, 0
	v_mov_b32_e32 v25, 0
	v_mov_b32_e32 v26, 0
	v_mov_b32_e32 v27, 0
	v_mov_b32_e32 v28, 0
	v_mov_b32_e32 v29, 0
	v_mov_b32_e32 v30, 0
	v_mov_b32_e32 v31, 0
	v_mov_b32_e32 v32, 0
	v_mov_b32_e32 v33, 0
	v_mov_b32_e32 v34, 0
	v_mov_b32_e32 v35, 0
	v_mov_b32_e32 v36, 0
	v_mov_b32_e32 v37, 0
	v_mov_b32_e32 v38, 0
	v_mov_b32_e32 v39, 0
	v_mov_b32_e32 v40, 0
	v_mov_b32_e32 v41, 0
	v_mov_b32_e32 v42, 0
	v_mov_b32_e32 v43, 0
	v_mov_b32_e32 v44, 0
	v_mov_b32_e32 v45, 0
	v_mov_b32_e32 v46, 0
	v_mov_b32_e32 v47, 0
	v_mov_b32_e32 v48, 0
	v_mov_b32_e32 v49, 0
	v_mov_b32_e32 v50, 0
	v_mov_b32_e32 v51, 0
	v_mov_b32_e32 v52, 0
	v_mov_b32_e32 v53, 0
	v_mov_b32_e32 v54, 0
	v_mov_b32_e32 v55, 0
	v_mov_b32_e32 v56, 0
	v_mov_b32_e32 v57, 0
	v_mov_b32_e32 v58, 0
	v_mov_b32_e32 v59, 0
	v_mov_b32_e32 v60, 0
	v_mov_b32_e32 v61, 0
	v_mov_b32_e32 v62, 0
	v_mov_b32_e32 v63, 0
	v_mov_b32_e32 v64, 0
	v_mov_b32_e32 v65, 0
	v_mov_b32_e32 v66, 0
	v_mov_b32_e32 v67, 0
	v_mov_b32_e32 v68, 0
	v_mov_b32_e32 v69, 0
	v_mov_b32_e32 v70, 0
	v_mov_b32_e32 v71, 0
	v_mov_b32_e32 v72, 0
	v_mov_b32_e32 v73, 0
	v_mov_b32_e32 v74, 0
	v_mov_b32_e32 v75, 0
	v_mov_b32_e32 v76, 0
	v_mov_b32_e32 v77, 0
	v_mov_b32_e32 v78, 0
	v_mov_b32_e32 v79, 0
	v_mov_b32_e32 v80, 0
	v_mov_b32_e32 v81, 0
	v_mov_b32_e32 v82, 0
	v_mov_b32_e32 v83, 0
	v_mov_b32_e32 v84, 0
	v_mov_b32_e32 v85, 0
	v_mov_b32_e32 v86, 0
	v_mov_b32_e32 v87, 0
	v_mov_b32_e32 v88, 0
	v_mov_b32_e32 v89, 0
	v_mov_b32_e32 v90, 0
	v_mov_b32_e32 v91, 0
	v_mov_b32_e32 v92, 0
	v_mov_b32_e32 v93, 0
	v_mov_b32_e32 v94, 0
	v_mov_b32_e32 v95, 0
	v_mov_b32_e32 v96, 0
	v_mov_b32_e32 v97, 0
	v_mov_b32_e32 v98, 0
	v_mov_b32_e32 v99, 0
	v_mov_b32_e32 v100, 0
	v_mov_b32_e32 v101, 0
	v_mov_b32_e32 v102, 0
	v_mov_b32_e32 v103, 0
	v_mov_b32_e32 v104, 0
	v_mov_b32_e32 v105, 0
	v_mov_b32_e32 v106, 0
	v_mov_b32_e32 v107, 0
	v_mov_b32_e32 v108, 0
	v_mov_b32_e32 v109, 0
	v_mov_b32_e32 v110, 0
	v_mov_b32_e32 v111, 0
	v_mov_b32_e32 v112, 0
	v_mov_b32_e32 v113, 0
	v_mov_b32_e32 v114, 0
	v_mov_b32_e32 v115, 0
	v_mov_b32_e32 v116, 0
	v_mov_b32_e32 v117, 0
	v_mov_b32_e32 v118, 0
	v_mov_b32_e32 v119, 0
	v_mov_b32_e32 v120, 0
	v_mov_b32_e32 v121, 0
	v_mov_b32_e32 v122, 0
	v_mov_b32_e32 v123, 0
	v_mov_b32_e32 v124, 0
	v_mov_b32_e32 v125, 0
	v_mov_b32_e32 v126, 0
	v_mov_b32_e32 v127, 0
	v_mov_b32_e32 v128, 0
	v_mov_b32_e32 v129, 0
	s_cbranch_scc1 .LBB0_168
	s_barrier
; DI int wave_of(int tid) { return __builtin_amdgcn_readfirstlane(tid >> 6); }
; #define STAGE_A(P, br, kt) do { const char* _g = (const char*)(A + (long)(br) * lda + (long)(kt) * BK); \
;     __builtin_amdgcn_global_load_lds((const unsigned*)(_g + (size_t)offA0), (unsigned*)((char*)(P) + sb0), 16, 0, 0); \
;     __builtin_amdgcn_global_load_lds((const unsigned*)(_g + (size_t)lda * 128 + (size_t)offA0), (unsigned*)((char*)(P) + sb1), 16, 0, 0); } while (0)
; #define STAGE_B(P, br, kt) do { const char* _g = (const char*)(B + (long)(br) * ldb + (long)(kt) * BK); \
;     __builtin_amdgcn_global_load_lds((const unsigned*)(_g + (size_t)offB0), (unsigned*)((char*)(P) + sb0), 16, 0, 0); \
;     __builtin_amdgcn_global_load_lds((const unsigned*)(_g + (size_t)ldb * 128 + (size_t)offB0), (unsigned*)((char*)(P) + sb1), 16, 0, 0); } while (0)
; #define WAIT_V(n) asm volatile("s_waitcnt vmcnt(" #n ")" ::: "memory")
; #define BAR __builtin_amdgcn_s_barrier()
; DI void gemm_core(WVP char* smem, const u16* __restrict__ A, int lda, int ar0, int ar1,
;                   const u16* __restrict__ B, int ldb, int bc0, int K, AccT& acc) {
;     ...
;   const int wid = wave_of(tid), lane = tid & 63, wr = wid >> 2, wc = wid & 3, fr = lane & 15, fq = lane >> 4;
;   const int sb0 = tid * 16, sb1 = sb0 + 8192;
;   int R0, C0; stage_rc(sb0, R0, C0);
;   const unsigned offA0 = (unsigned)(R0 * lda + C0) * 2u, offB0 = (unsigned)(R0 * ldb + C0) * 2u;
;   const int ac0 = ar0, ac1 = ar1, bb0 = bc0, bb1 = bc0 + HALF;
;   bf16x8 At[4][2], B0[2][2], B1[2][2];
;   const int nt = K / BK;
;   __syncthreads();
;   STAGE_B(SB(0, 0), bb0, 0); STAGE_A(SA(0, 0), ac0, 0);
;   STAGE_B(SB(0, 1), bb1, 0); STAGE_A(SA(0, 1), ac1, 0);
;   if (wr == 1) BAR;
;   WAIT_V(4); BAR;
;   STAGE_B(SB(1, 0), bb0, 1); STAGE_A(SA(1, 0), ac0, 1); STAGE_B(SB(1, 1), bb1, 1);
;   WAIT_V(6); BAR;
.LBB0_168:
	v_add_u32_e32 v141, s61, v12
	s_ashr_i32 s5, s1, 6
	v_readfirstlane_b32 s1, v141
	v_add_u32_e32 v142, 0x2000, v141
	v_lshl_add_u64 v[14:15], v[2:3], 0, s[64:65]
	s_mov_b32 m0, s1
	v_readfirstlane_b32 s1, v142
	v_add_u32_e32 v143, 0x8000, v135
	s_waitcnt vmcnt(4)
	s_barrier
	global_load_lds_dwordx4 v[14:15], off
	v_lshl_add_u64 v[2:3], v[2:3], 0, s[78:79]
	s_mov_b32 m0, s1
	v_readfirstlane_b32 s1, v143
	v_add_u32_e32 v144, 0xa000, v135
	global_load_lds_dwordx4 v[2:3], off
	v_lshl_add_u64 v[2:3], v[4:5], 0, s[64:65]
	s_mov_b32 m0, s1
	v_readfirstlane_b32 s1, v144
	v_add_u32_e32 v145, s84, v12
	global_load_lds_dwordx4 v[2:3], off
	v_lshl_add_u64 v[2:3], v[4:5], 0, s[78:79]
	s_mov_b32 m0, s1
	v_readfirstlane_b32 s1, v145
	v_add_u32_e32 v146, 0x2000, v145
	global_load_lds_dwordx4 v[2:3], off
	v_lshl_add_u64 v[2:3], v[6:7], 0, s[64:65]
	s_mov_b32 m0, s1
	v_readfirstlane_b32 s1, v146
	global_load_lds_dwordx4 v[2:3], off
	v_lshl_add_u64 v[2:3], v[6:7], 0, s[78:79]
	s_mov_b32 m0, s1
	v_and_b32_e32 v0, 15, v9
	global_load_lds_dwordx4 v[2:3], off
	v_lshlrev_b32_e32 v2, 2, v9
	v_and_b32_e32 v13, 48, v9
	v_lshlrev_b32_e32 v0, 6, v0
	v_and_b32_e32 v2, 32, v2
	s_lshl_b32 s1, s5, 12
	v_bitop3_b32 v0, v0, v2, v13 bitop3:0x36
	s_lshl_b32 s20, s0, 13
	s_and_b32 s19, s1, 0x3000
	v_add_u32_e32 v3, s9, v0
	s_or_b32 s0, s20, 0x800
	s_or_b32 s1, s20, 0x1000
	s_or_b32 s9, s20, 0x1800
	s_add_u32 s12, s54, s12
	s_addc_u32 s13, s55, s13
	s_sub_i32 s14, s14, s17
	s_lshl_b32 s15, s15, 9
	s_sub_i32 s14, s14, s15
	s_sext_i32_i16 s14, s14
	s_lshl_b32 s14, s14, 7
	s_add_i32 s16, s16, s14
	s_ashr_i32 s17, s16, 31
	v_add_u32_e32 v4, s60, v0
	v_add_u32_e32 v5, s61, v0
	v_add_u32_e32 v6, s84, v0
	v_add_u32_e32 v7, 0, v0
	v_lshlrev_b32_e32 v0, 6, v9
	s_lshl_b64 s[14:15], s[16:17], 11
	v_and_or_b32 v0, v0, s74, v13
	s_add_u32 s14, s54, s14
	v_xad_u32 v148, v0, v2, 0
	v_lshlrev_b32_e32 v0, 14, v8
	s_addc_u32 s15, s55, s15
	s_addk_i32 s16, 0xb00
	v_and_b32_e32 v0, 0xffff8000, v0
	s_ashr_i32 s17, s16, 31
	s_waitcnt vmcnt(6)
	v_lshl_add_u32 v0, v10, 11, v0
	v_and_b32_e32 v2, 1, v8
	s_lshl_b64 s[16:17], s[16:17], 11
	v_lshl_or_b32 v0, v2, 6, v0
	s_add_u32 s16, s54, s16
	v_mov_b32_e32 v2, 0
	v_lshl_add_u32 v0, v11, 1, v0
	s_addc_u32 s17, s55, s17
	s_mov_b32 s18, -2
	v_add_u32_e32 v149, s19, v3
	v_add_u32_e32 v132, s20, v7
	v_add_u32_e32 v147, s19, v4
	v_add_u32_e32 v137, s19, v5
	v_add_u32_e32 v134, s19, v6
	v_mov_b32_e32 v3, v2
	v_mov_b32_e32 v4, v2
	v_mov_b32_e32 v5, v2
	v_mov_b32_e32 v6, v2
	v_mov_b32_e32 v7, v2
	v_mov_b32_e32 v8, v2
	v_mov_b32_e32 v9, v2
	v_mov_b32_e32 v10, v2
	v_mov_b32_e32 v11, v2
	v_mov_b32_e32 v12, v2
	v_mov_b32_e32 v13, v2
	v_mov_b32_e32 v14, v2
	v_mov_b32_e32 v15, v2
	s_mov_b64 s[22:23], 0x1e880100
	s_mov_b64 s[24:25], 0x1e8a0100
	s_barrier

; DI int get_tid(int wv) { int l; asm volatile("v_mbcnt_lo_u32_b32 %0, -1, 0\n\tv_mbcnt_hi_u32_b32 %0, -1, %0" : "=v"(l)); return wv * 64 + l; }
; DI int wave_of(int tid) { return __builtin_amdgcn_readfirstlane(tid >> 6); }
; #define STAGE_A(P, br, kt) do { const char* _g = (const char*)(A + (long)(br) * lda + (long)(kt) * BK); \
;     __builtin_amdgcn_global_load_lds((const unsigned*)(_g + (size_t)offA0), (unsigned*)((char*)(P) + sb0), 16, 0, 0); \
;     __builtin_amdgcn_global_load_lds((const unsigned*)(_g + (size_t)lda * 128 + (size_t)offA0), (unsigned*)((char*)(P) + sb1), 16, 0, 0); } while (0)
; #define STAGE_B(P, br, kt) do { const char* _g = (const char*)(B + (long)(br) * ldb + (long)(kt) * BK); \
;     __builtin_amdgcn_global_load_lds((const unsigned*)(_g + (size_t)offB0), (unsigned*)((char*)(P) + sb0), 16, 0, 0); \
;     __builtin_amdgcn_global_load_lds((const unsigned*)(_g + (size_t)ldb * 128 + (size_t)offB0), (unsigned*)((char*)(P) + sb1), 16, 0, 0); } while (0)
; #define BAR __builtin_amdgcn_s_barrier()
; DI void gemm_core(WVP char* smem, const u16* __restrict__ A, int lda, int ar0, int ar1,
;                   const u16* __restrict__ B, int ldb, int bc0, int K, AccT& acc) {
;     ...
;   const int tid = get_tid(WV);
;   const int wid = wave_of(tid), lane = tid & 63, wr = wid >> 2, wc = wid & 3, fr = lane & 15, fq = lane >> 4;
;   const int sb0 = tid * 16, sb1 = sb0 + 8192;
;   int R0, C0; stage_rc(sb0, R0, C0);
;   const unsigned offA0 = (unsigned)(R0 * lda + C0) * 2u, offB0 = (unsigned)(R0 * ldb + C0) * 2u;
;   const int ac0 = ar0, ac1 = ar1, bb0 = bc0, bb1 = bc0 + HALF;
;   bf16x8 At[4][2], B0[2][2], B1[2][2];
;   const int nt = K / BK;
;   __syncthreads();
;   STAGE_B(SB(0, 0), bb0, 0); STAGE_A(SA(0, 0), ac0, 0);
;   STAGE_B(SB(0, 1), bb1, 0); STAGE_A(SA(0, 1), ac1, 0);
;   if (wr == 1) BAR;
.LBB0_184:
	s_add_i32 s0, s1, s8
	s_ashr_i32 s1, s0, 31
	s_lshr_b32 s1, s1, 23
	s_add_i32 s1, s0, s1
	s_ashr_i32 s8, s1, 9
	s_and_b32 s1, s1, 0xfe00
	s_sub_i32 s0, s0, s1
	s_sext_i32_i16 s1, s0
	s_bfe_u32 s1, s1, 0x2001d
	v_mbcnt_lo_u32_b32 v9, -1, 0
	v_mbcnt_hi_u32_b32 v9, -1, v9
	s_add_i32 s1, s0, s1
	v_add_u32_e32 v0, s3, v9
	v_ashrrev_i32_e32 v2, 31, v0
	s_lshl_b32 s26, s8, 2
	s_sext_i32_i16 s8, s1
	s_and_b32 s1, s1, 0xfffc
	v_lshrrev_b32_e32 v2, 26, v2
	s_sub_i32 s0, s0, s1
	v_readfirstlane_b32 s1, v0
	v_lshlrev_b32_e32 v12, 4, v0
	v_add_u32_e32 v2, v0, v2
	v_bfe_i32 v0, v0, 27, 1
	v_lshrrev_b32_e32 v0, 22, v0
	v_add_u32_e32 v0, v12, v0
	v_and_b32_e32 v0, 0xfffffc00, v0
	v_sub_u32_e32 v0, v12, v0
	v_ashrrev_i32_e32 v8, 6, v2
	v_lshrrev_b32_e32 v2, 4, v0
	v_bitop3_b32 v0, v2, v0, 32 bitop3:0x6c
	s_sext_i32_i16 s0, s0
	s_ashr_i32 s27, s8, 2
	v_ashrrev_i32_e32 v3, 31, v0
	s_add_i32 s26, s26, s0
	s_lshl_b32 s14, s27, 8
	v_lshrrev_b32_e32 v3, 26, v3
	s_lshl_b32 s16, s26, 8
	v_add_u32_e32 v3, v0, v3
	s_ashr_i32 s15, s14, 31
	s_or_b32 s22, s16, 0x80
	s_ashr_i32 s0, s1, 8
	v_ashrrev_i32_e32 v10, 6, v3
	v_and_b32_e32 v3, 0xc0, v3
	s_or_b32 s28, s14, 0x80
	s_lshl_b64 s[8:9], s[14:15], 11
	v_sub_u32_e32 v0, v0, v3
	s_add_u32 s18, s10, s8
	v_lshlrev_b32_e32 v2, 3, v8
	v_lshlrev_b32_e32 v4, 5, v8
	v_ashrrev_i16_sdwa v0, v254, sext(v0) dst_sel:DWORD dst_unused:UNUSED_PAD src0_sel:DWORD src1_sel:BYTE_0
	s_addc_u32 s19, s11, s9
	s_add_i32 s20, 0, 0x10000
	v_and_b32_e32 v2, 0x1ffff0, v2
	v_and_b32_e32 v4, 32, v4
	v_bfe_i32 v11, v0, 0, 16
	v_add_u32_e32 v134, s20, v12
	v_add_u32_e32 v0, v4, v11
	v_add_lshl_u32 v2, v10, v2, 11
	v_readfirstlane_b32 s15, v134
	v_lshl_add_u32 v0, v0, 1, v2
	s_mov_b32 m0, s15
	s_ashr_i32 s17, s16, 31
	s_barrier
	v_lshl_add_u64 v[2:3], s[18:19], 0, v[0:1]
	global_load_lds_dwordx4 v0, s[18:19]
	s_lshl_b64 s[18:19], s[16:17], 11
	v_add_u32_e32 v13, 0x2000, v12
	s_add_u32 s30, s75, s18
	v_readlane_b32 s21, v255, 37
	v_add_u32_e32 v6, s20, v13
	s_addc_u32 s31, s21, s19
	s_ashr_i32 s29, s28, 31
	v_readfirstlane_b32 s15, v6
	v_add_u32_e32 v135, 0, v12
	s_lshl_b64 s[28:29], s[28:29], 11
	v_lshl_add_u64 v[4:5], v[2:3], 0, s[76:77]
	s_mov_b32 m0, s15
	v_readfirstlane_b32 s15, v135
	v_add_u32_e32 v136, 0x2000, v135
	s_add_u32 s28, s10, s28
	global_load_lds_dwordx4 v[4:5], off
	v_lshl_add_u64 v[4:5], s[30:31], 0, v[0:1]
	s_mov_b32 m0, s15
	v_readfirstlane_b32 s15, v136
	s_addc_u32 s29, s11, s29
	v_add_u32_e32 v138, s60, v12
	s_ashr_i32 s23, s22, 31
	global_load_lds_dwordx4 v0, s[30:31]
	v_lshl_add_u64 v[6:7], v[4:5], 0, s[76:77]
	s_mov_b32 m0, s15
	v_readfirstlane_b32 s15, v138
	v_add_u32_e32 v13, s60, v13
	s_lshl_b64 s[22:23], s[22:23], 11
	global_load_lds_dwordx4 v[6:7], off
	v_lshl_add_u64 v[6:7], s[28:29], 0, v[0:1]
	s_mov_b32 m0, s15
	v_readfirstlane_b32 s15, v13
	s_add_u32 s22, s75, s22
	v_add_u32_e32 v139, 0x4000, v135
	global_load_lds_dwordx4 v0, s[28:29]
	v_lshl_add_u64 v[14:15], v[6:7], 0, s[76:77]
	s_mov_b32 m0, s15
	s_addc_u32 s23, s21, s23
	v_readfirstlane_b32 s15, v139
	v_add_u32_e32 v140, 0x6000, v135
	global_load_lds_dwordx4 v[14:15], off
	v_lshl_add_u64 v[130:131], s[22:23], 0, v[0:1]
	s_mov_b32 m0, s15
	v_readfirstlane_b32 s15, v140
	global_load_lds_dwordx4 v0, s[22:23]
	v_lshl_add_u64 v[14:15], v[130:131], 0, s[76:77]
	s_mov_b32 m0, s15
	s_cmp_lg_u32 s0, 1
	global_load_lds_dwordx4 v[14:15], off
	v_mov_b32_e32 v16, 0
	v_mov_b32_e32 v17, 0
	v_mov_b32_e32 v18, 0
	v_mov_b32_e32 v19, 0
	v_mov_b32_e32 v20, 0
	v_mov_b32_e32 v21, 0
	v_mov_b32_e32 v22, 0
	v_mov_b32_e32 v23, 0
	v_mov_b32_e32 v24, 0
	v_mov_b32_e32 v25, 0
	v_mov_b32_e32 v26, 0
	v_mov_b32_e32 v27, 0
	v_mov_b32_e32 v28, 0
	v_mov_b32_e32 v29, 0
	v_mov_b32_e32 v30, 0
	v_mov_b32_e32 v31, 0
	v_mov_b32_e32 v32, 0
	v_mov_b32_e32 v33, 0
	v_mov_b32_e32 v34, 0
	v_mov_b32_e32 v35, 0
	v_mov_b32_e32 v36, 0
	v_mov_b32_e32 v37, 0
	v_mov_b32_e32 v38, 0
	v_mov_b32_e32 v39, 0
	v_mov_b32_e32 v40, 0
	v_mov_b32_e32 v41, 0
	v_mov_b32_e32 v42, 0
	v_mov_b32_e32 v43, 0
	v_mov_b32_e32 v44, 0
	v_mov_b32_e32 v45, 0
	v_mov_b32_e32 v46, 0
	v_mov_b32_e32 v47, 0
	v_mov_b32_e32 v48, 0
	v_mov_b32_e32 v49, 0
	v_mov_b32_e32 v50, 0
	v_mov_b32_e32 v51, 0
	v_mov_b32_e32 v52, 0
	v_mov_b32_e32 v53, 0
	v_mov_b32_e32 v54, 0
	v_mov_b32_e32 v55, 0
	v_mov_b32_e32 v56, 0
	v_mov_b32_e32 v57, 0
	v_mov_b32_e32 v58, 0
	v_mov_b32_e32 v59, 0
	v_mov_b32_e32 v60, 0
	v_mov_b32_e32 v61, 0
	v_mov_b32_e32 v62, 0
	v_mov_b32_e32 v63, 0
	v_mov_b32_e32 v64, 0
	v_mov_b32_e32 v65, 0
	v_mov_b32_e32 v66, 0
	v_mov_b32_e32 v67, 0
	v_mov_b32_e32 v68, 0
	v_mov_b32_e32 v69, 0
	v_mov_b32_e32 v70, 0
	v_mov_b32_e32 v71, 0
	v_mov_b32_e32 v72, 0
	v_mov_b32_e32 v73, 0
	v_mov_b32_e32 v74, 0
	v_mov_b32_e32 v75, 0
	v_mov_b32_e32 v76, 0
	v_mov_b32_e32 v77, 0
	v_mov_b32_e32 v78, 0
	v_mov_b32_e32 v79, 0
	v_mov_b32_e32 v80, 0
	v_mov_b32_e32 v81, 0
	v_mov_b32_e32 v82, 0
	v_mov_b32_e32 v83, 0
	v_mov_b32_e32 v84, 0
	v_mov_b32_e32 v85, 0
	v_mov_b32_e32 v86, 0
	v_mov_b32_e32 v87, 0
	v_mov_b32_e32 v88, 0
	v_mov_b32_e32 v89, 0
	v_mov_b32_e32 v90, 0
	v_mov_b32_e32 v91, 0
	v_mov_b32_e32 v92, 0
	v_mov_b32_e32 v93, 0
	v_mov_b32_e32 v94, 0
	v_mov_b32_e32 v95, 0
	v_mov_b32_e32 v96, 0
	v_mov_b32_e32 v97, 0
	v_mov_b32_e32 v98, 0
	v_mov_b32_e32 v99, 0
	v_mov_b32_e32 v100, 0
	v_mov_b32_e32 v101, 0
	v_mov_b32_e32 v102, 0
	v_mov_b32_e32 v103, 0
	v_mov_b32_e32 v104, 0
	v_mov_b32_e32 v105, 0
	v_mov_b32_e32 v106, 0
	v_mov_b32_e32 v107, 0
	v_mov_b32_e32 v108, 0
	v_mov_b32_e32 v109, 0
	v_mov_b32_e32 v110, 0
	v_mov_b32_e32 v111, 0
	v_mov_b32_e32 v112, 0
	v_mov_b32_e32 v113, 0
	v_mov_b32_e32 v114, 0
	v_mov_b32_e32 v115, 0
	v_mov_b32_e32 v116, 0
	v_mov_b32_e32 v117, 0
	v_mov_b32_e32 v118, 0
	v_mov_b32_e32 v119, 0
	v_mov_b32_e32 v120, 0
	v_mov_b32_e32 v121, 0
	v_mov_b32_e32 v122, 0
	v_mov_b32_e32 v123, 0
	v_mov_b32_e32 v124, 0
	v_mov_b32_e32 v125, 0
	v_mov_b32_e32 v126, 0
	v_mov_b32_e32 v127, 0
	v_mov_b32_e32 v128, 0
	v_mov_b32_e32 v129, 0
	s_cbranch_scc1 .LBB0_186
	s_barrier
; DI int wave_of(int tid) { return __builtin_amdgcn_readfirstlane(tid >> 6); }
; #define STAGE_A(P, br, kt) do { const char* _g = (const char*)(A + (long)(br) * lda + (long)(kt) * BK); \
;     __builtin_amdgcn_global_load_lds((const unsigned*)(_g + (size_t)offA0), (unsigned*)((char*)(P) + sb0), 16, 0, 0); \
;     __builtin_amdgcn_global_load_lds((const unsigned*)(_g + (size_t)lda * 128 + (size_t)offA0), (unsigned*)((char*)(P) + sb1), 16, 0, 0); } while (0)
; #define STAGE_B(P, br, kt) do { const char* _g = (const char*)(B + (long)(br) * ldb + (long)(kt) * BK); \
;     __builtin_amdgcn_global_load_lds((const unsigned*)(_g + (size_t)offB0), (unsigned*)((char*)(P) + sb0), 16, 0, 0); \
;     __builtin_amdgcn_global_load_lds((const unsigned*)(_g + (size_t)ldb * 128 + (size_t)offB0), (unsigned*)((char*)(P) + sb1), 16, 0, 0); } while (0)
; #define WAIT_V(n) asm volatile("s_waitcnt vmcnt(" #n ")" ::: "memory")
; #define BAR __builtin_amdgcn_s_barrier()
; DI void gemm_core(WVP char* smem, const u16* __restrict__ A, int lda, int ar0, int ar1,
;                   const u16* __restrict__ B, int ldb, int bc0, int K, AccT& acc) {
;     ...
;   const int wid = wave_of(tid), lane = tid & 63, wr = wid >> 2, wc = wid & 3, fr = lane & 15, fq = lane >> 4;
;   const int sb0 = tid * 16, sb1 = sb0 + 8192;
;   int R0, C0; stage_rc(sb0, R0, C0);
;   const unsigned offA0 = (unsigned)(R0 * lda + C0) * 2u, offB0 = (unsigned)(R0 * ldb + C0) * 2u;
;   const int ac0 = ar0, ac1 = ar1, bb0 = bc0, bb1 = bc0 + HALF;
;   bf16x8 At[4][2], B0[2][2], B1[2][2];
;   const int nt = K / BK;
;   __syncthreads();
;   STAGE_B(SB(0, 0), bb0, 0); STAGE_A(SA(0, 0), ac0, 0);
;   STAGE_B(SB(0, 1), bb1, 0); STAGE_A(SA(0, 1), ac1, 0);
;   if (wr == 1) BAR;
;   WAIT_V(4); BAR;
;   STAGE_B(SB(1, 0), bb0, 1); STAGE_A(SA(1, 0), ac0, 1); STAGE_B(SB(1, 1), bb1, 1);
;   WAIT_V(6); BAR;
.LBB0_186:
	v_add_u32_e32 v141, s61, v12
	s_ashr_i32 s15, s1, 6
	v_readfirstlane_b32 s1, v141
	v_add_u32_e32 v142, 0x2000, v141
	v_lshl_add_u64 v[14:15], v[2:3], 0, s[64:65]
	s_mov_b32 m0, s1
	v_readfirstlane_b32 s1, v142
	v_add_u32_e32 v143, 0x8000, v135
	s_waitcnt vmcnt(4)
	s_barrier
	global_load_lds_dwordx4 v[14:15], off
	v_lshl_add_u64 v[2:3], v[2:3], 0, s[78:79]
	s_mov_b32 m0, s1
	v_readfirstlane_b32 s1, v143
	v_add_u32_e32 v144, 0xa000, v135
	global_load_lds_dwordx4 v[2:3], off
	v_lshl_add_u64 v[2:3], v[4:5], 0, s[64:65]
	s_mov_b32 m0, s1
	v_readfirstlane_b32 s1, v144
	v_add_u32_e32 v145, s84, v12
	global_load_lds_dwordx4 v[2:3], off
	v_lshl_add_u64 v[2:3], v[4:5], 0, s[78:79]
	s_mov_b32 m0, s1
	v_readfirstlane_b32 s1, v145
	v_add_u32_e32 v147, 0x2000, v145
	global_load_lds_dwordx4 v[2:3], off
	v_lshl_add_u64 v[2:3], v[6:7], 0, s[64:65]
	s_mov_b32 m0, s1
	v_readfirstlane_b32 s1, v147
	global_load_lds_dwordx4 v[2:3], off
	v_lshl_add_u64 v[2:3], v[6:7], 0, s[78:79]
	s_mov_b32 m0, s1
	v_and_b32_e32 v0, 15, v9
	global_load_lds_dwordx4 v[2:3], off
	v_lshlrev_b32_e32 v2, 2, v9
	v_and_b32_e32 v13, 48, v9
	v_lshlrev_b32_e32 v0, 6, v0
	v_and_b32_e32 v2, 32, v2
	v_bitop3_b32 v0, v0, v2, v13 bitop3:0x36
	v_add_u32_e32 v3, s20, v0
	v_add_u32_e32 v4, s60, v0
	v_add_u32_e32 v5, s61, v0
	v_add_u32_e32 v6, s84, v0
	v_add_u32_e32 v7, 0, v0
	v_lshlrev_b32_e32 v0, 6, v9
	s_lshl_b32 s1, s15, 12
	s_lshl_b32 s23, s0, 13
	v_and_or_b32 v0, v0, s74, v13
	s_and_b32 s22, s1, 0x3000
	v_xad_u32 v148, v0, v2, 0
	s_or_b32 s0, s23, 0x800
	s_or_b32 s1, s23, 0x1000
	s_or_b32 s20, s23, 0x1800
	v_lshlrev_b32_e32 v0, 14, v8
	v_and_b32_e32 v0, 0xffff8000, v0
	s_add_u32 s8, s54, s8
	s_waitcnt vmcnt(6)
	v_lshl_add_u32 v0, v10, 11, v0
	v_and_b32_e32 v2, 1, v8
	s_addc_u32 s9, s55, s9
	v_lshl_or_b32 v0, v2, 6, v0
	s_add_u32 s18, s54, s18
	v_mov_b32_e32 v2, 0
	v_lshl_add_u32 v0, v11, 1, v0
	s_addc_u32 s19, s55, s19
	s_mov_b32 s21, -2
	v_add_u32_e32 v149, s22, v3
	v_add_u32_e32 v132, s23, v7
	v_add_u32_e32 v146, s22, v4
	v_add_u32_e32 v137, s22, v5
	v_add_u32_e32 v133, s22, v6
	v_mov_b32_e32 v3, v2
	v_mov_b32_e32 v4, v2
	v_mov_b32_e32 v5, v2
	v_mov_b32_e32 v6, v2
	v_mov_b32_e32 v7, v2
	v_mov_b32_e32 v8, v2
	v_mov_b32_e32 v9, v2
	v_mov_b32_e32 v10, v2
	v_mov_b32_e32 v11, v2
	v_mov_b32_e32 v12, v2
	v_mov_b32_e32 v13, v2
	v_mov_b32_e32 v14, v2
	v_mov_b32_e32 v15, v2
	s_barrier

; DI int get_tid(int wv) { int l; asm volatile("v_mbcnt_lo_u32_b32 %0, -1, 0\n\tv_mbcnt_hi_u32_b32 %0, -1, %0" : "=v"(l)); return wv * 64 + l; }
; DI int wave_of(int tid) { return __builtin_amdgcn_readfirstlane(tid >> 6); }
; #define STAGE_A(P, br, kt) do { const char* _g = (const char*)(A + (long)(br) * lda + (long)(kt) * BK); \
;     __builtin_amdgcn_global_load_lds((const unsigned*)(_g + (size_t)offA0), (unsigned*)((char*)(P) + sb0), 16, 0, 0); \
;     __builtin_amdgcn_global_load_lds((const unsigned*)(_g + (size_t)lda * 128 + (size_t)offA0), (unsigned*)((char*)(P) + sb1), 16, 0, 0); } while (0)
; #define STAGE_B(P, br, kt) do { const char* _g = (const char*)(B + (long)(br) * ldb + (long)(kt) * BK); \
;     __builtin_amdgcn_global_load_lds((const unsigned*)(_g + (size_t)offB0), (unsigned*)((char*)(P) + sb0), 16, 0, 0); \
;     __builtin_amdgcn_global_load_lds((const unsigned*)(_g + (size_t)ldb * 128 + (size_t)offB0), (unsigned*)((char*)(P) + sb1), 16, 0, 0); } while (0)
; #define BAR __builtin_amdgcn_s_barrier()
; DI void gemm_core(WVP char* smem, const u16* __restrict__ A, int lda, int ar0, int ar1,
;                   const u16* __restrict__ B, int ldb, int bc0, int K, AccT& acc) {
;     ...
;   const int tid = get_tid(WV);
;   const int wid = wave_of(tid), lane = tid & 63, wr = wid >> 2, wc = wid & 3, fr = lane & 15, fq = lane >> 4;
;   const int sb0 = tid * 16, sb1 = sb0 + 8192;
;   int R0, C0; stage_rc(sb0, R0, C0);
;   const unsigned offA0 = (unsigned)(R0 * lda + C0) * 2u, offB0 = (unsigned)(R0 * ldb + C0) * 2u;
;   const int ac0 = ar0, ac1 = ar1, bb0 = bc0, bb1 = bc0 + HALF;
;   bf16x8 At[4][2], B0[2][2], B1[2][2];
;   const int nt = K / BK;
;   __syncthreads();
;   STAGE_B(SB(0, 0), bb0, 0); STAGE_A(SA(0, 0), ac0, 0);
;   STAGE_B(SB(0, 1), bb1, 0); STAGE_A(SA(0, 1), ac1, 0);
;   if (wr == 1) BAR;
; __global__ void __launch_bounds__(NTHR) mega(Params p) {
;     ...
;           for (int b = 0; b < 4; ++b) {
;             const int q = pr * 3 + b;
;             u16* sd = (b == 3) ? mg + pr * 256 : proj + (q < 8 ? 768 + 256 * q : (q < 10 ? 256 * (q - 8) : 3840 + 256 * (q - 10)));
;             EpiSig E1{sd, b == 3 ? DM : INW, pc * 256};
;             gemm_tile(WV, smem, WG + (size_t)b * DM * DM, DM, pr * 256, pr * 256 + 128, xn, DM, pc * 256, DM, E1);
.LBB0_224:
	v_mbcnt_lo_u32_b32 v5, -1, 0
	v_mbcnt_hi_u32_b32 v5, -1, v5
	s_lshl_b32 s0, s21, 21
	v_add_u32_e32 v0, s3, v5
	v_ashrrev_i32_e32 v2, 31, v0
	v_lshrrev_b32_e32 v2, 26, v2
	v_readfirstlane_b32 s1, v0
	v_lshlrev_b32_e32 v8, 4, v0
	v_add_u32_e32 v2, v0, v2
	v_bfe_i32 v0, v0, 27, 1
	v_lshrrev_b32_e32 v0, 22, v0
	v_add_u32_e32 v0, v8, v0
	v_and_b32_e32 v0, 0xfffffc00, v0
	v_sub_u32_e32 v0, v8, v0
	v_ashrrev_i32_e32 v4, 6, v2
	v_lshrrev_b32_e32 v2, 4, v0
	v_bitop3_b32 v0, v2, v0, 32 bitop3:0x6c
	v_ashrrev_i32_e32 v3, 31, v0
	v_lshrrev_b32_e32 v3, 26, v3
	v_add_u32_e32 v3, v0, v3
	v_ashrrev_i32_e32 v6, 6, v3
	v_and_b32_e32 v3, 0xc0, v3
	v_sub_u32_e32 v0, v0, v3
	s_add_u32 s47, s5, s0
	v_lshlrev_b32_e32 v2, 3, v4
	v_lshlrev_b32_e32 v7, 5, v4
	v_ashrrev_i16_sdwa v0, v254, sext(v0) dst_sel:DWORD dst_unused:UNUSED_PAD src0_sel:DWORD src1_sel:BYTE_0
	s_addc_u32 s50, s50, 0
	v_and_b32_e32 v2, 0x1ffff0, v2
	v_and_b32_e32 v10, 32, v7
	v_bfe_i32 v7, v0, 0, 16
	s_add_i32 s5, 0, 0x10000
	v_add_u32_e32 v9, 0x2000, v8
	v_add_u32_e32 v0, v10, v7
	v_add_lshl_u32 v2, v6, v2, 11
	v_add_u32_e32 v134, s5, v8
	v_lshl_add_u32 v0, v0, 1, v2
	v_readfirstlane_b32 s52, v134
	v_add_u32_e32 v2, s5, v9
	s_ashr_i32 s0, s1, 8
	s_mov_b32 m0, s52
	v_readfirstlane_b32 s52, v2
	v_add_u32_e32 v136, 0, v8
	s_barrier
	global_load_lds_dwordx4 v0, s[22:23]
	s_mov_b32 m0, s52
	s_add_u32 s52, s47, s26
	v_readfirstlane_b32 s57, v136
	global_load_lds_dwordx4 v0, s[24:25]
	s_addc_u32 s53, s50, s27
	s_mov_b32 m0, s57
	v_add_u32_e32 v137, 0x2000, v136
	v_lshl_add_u64 v[2:3], s[52:53], 0, v[0:1]
	global_load_lds_dwordx4 v0, s[52:53]
	v_readfirstlane_b32 s52, v137
	v_add_u32_e32 v138, s60, v8
	v_lshl_add_u64 v[10:11], v[2:3], 0, s[76:77]
	s_mov_b32 m0, s52
	v_readfirstlane_b32 s52, v138
	v_add_u32_e32 v9, s60, v9
	global_load_lds_dwordx4 v[10:11], off
	s_mov_b32 m0, s52
	v_readfirstlane_b32 s52, v9
	global_load_lds_dwordx4 v0, s[28:29]
	s_mov_b32 m0, s52
	s_add_u32 s52, s47, s34
	v_add_u32_e32 v139, 0x4000, v136
	s_addc_u32 s53, s50, s35
	v_readfirstlane_b32 s47, v139
	v_add_u32_e32 v140, 0x6000, v136
	global_load_lds_dwordx4 v0, s[30:31]
	v_lshl_add_u64 v[130:131], s[52:53], 0, v[0:1]
	s_mov_b32 m0, s47
	v_readfirstlane_b32 s47, v140
	global_load_lds_dwordx4 v0, s[52:53]
	v_lshl_add_u64 v[10:11], v[130:131], 0, s[76:77]
	s_mov_b32 m0, s47
	s_cmp_lg_u32 s0, 1
	global_load_lds_dwordx4 v[10:11], off
	v_mov_b32_e32 v16, 0
	v_mov_b32_e32 v17, 0
	v_mov_b32_e32 v18, 0
	v_mov_b32_e32 v19, 0
	v_mov_b32_e32 v20, 0
	v_mov_b32_e32 v21, 0
	v_mov_b32_e32 v22, 0
	v_mov_b32_e32 v23, 0
	v_mov_b32_e32 v24, 0
	v_mov_b32_e32 v25, 0
	v_mov_b32_e32 v26, 0
	v_mov_b32_e32 v27, 0
	v_mov_b32_e32 v28, 0
	v_mov_b32_e32 v29, 0
	v_mov_b32_e32 v30, 0
	v_mov_b32_e32 v31, 0
	v_mov_b32_e32 v32, 0
	v_mov_b32_e32 v33, 0
	v_mov_b32_e32 v34, 0
	v_mov_b32_e32 v35, 0
	v_mov_b32_e32 v36, 0
	v_mov_b32_e32 v37, 0
	v_mov_b32_e32 v38, 0
	v_mov_b32_e32 v39, 0
	v_mov_b32_e32 v40, 0
	v_mov_b32_e32 v41, 0
	v_mov_b32_e32 v42, 0
	v_mov_b32_e32 v43, 0
	v_mov_b32_e32 v44, 0
	v_mov_b32_e32 v45, 0
	v_mov_b32_e32 v46, 0
	v_mov_b32_e32 v47, 0
	v_mov_b32_e32 v48, 0
	v_mov_b32_e32 v49, 0
	v_mov_b32_e32 v50, 0
	v_mov_b32_e32 v51, 0
	v_mov_b32_e32 v52, 0
	v_mov_b32_e32 v53, 0
	v_mov_b32_e32 v54, 0
	v_mov_b32_e32 v55, 0
	v_mov_b32_e32 v56, 0
	v_mov_b32_e32 v57, 0
	v_mov_b32_e32 v58, 0
	v_mov_b32_e32 v59, 0
	v_mov_b32_e32 v60, 0
	v_mov_b32_e32 v61, 0
	v_mov_b32_e32 v62, 0
	v_mov_b32_e32 v63, 0
	v_mov_b32_e32 v64, 0
	v_mov_b32_e32 v65, 0
	v_mov_b32_e32 v66, 0
	v_mov_b32_e32 v67, 0
	v_mov_b32_e32 v68, 0
	v_mov_b32_e32 v69, 0
	v_mov_b32_e32 v70, 0
	v_mov_b32_e32 v71, 0
	v_mov_b32_e32 v72, 0
	v_mov_b32_e32 v73, 0
	v_mov_b32_e32 v74, 0
	v_mov_b32_e32 v75, 0
	v_mov_b32_e32 v76, 0
	v_mov_b32_e32 v77, 0
	v_mov_b32_e32 v78, 0
	v_mov_b32_e32 v79, 0
	v_mov_b32_e32 v80, 0
	v_mov_b32_e32 v81, 0
	v_mov_b32_e32 v82, 0
	v_mov_b32_e32 v83, 0
	v_mov_b32_e32 v84, 0
	v_mov_b32_e32 v85, 0
	v_mov_b32_e32 v86, 0
	v_mov_b32_e32 v87, 0
	v_mov_b32_e32 v88, 0
	v_mov_b32_e32 v89, 0
	v_mov_b32_e32 v90, 0
	v_mov_b32_e32 v91, 0
	v_mov_b32_e32 v92, 0
	v_mov_b32_e32 v93, 0
	v_mov_b32_e32 v94, 0
	v_mov_b32_e32 v95, 0
	v_mov_b32_e32 v96, 0
	v_mov_b32_e32 v97, 0
	v_mov_b32_e32 v98, 0
	v_mov_b32_e32 v99, 0
	v_mov_b32_e32 v100, 0
	v_mov_b32_e32 v101, 0
	v_mov_b32_e32 v102, 0
	v_mov_b32_e32 v103, 0
	v_mov_b32_e32 v104, 0
	v_mov_b32_e32 v105, 0
	v_mov_b32_e32 v106, 0
	v_mov_b32_e32 v107, 0
	v_mov_b32_e32 v108, 0
	v_mov_b32_e32 v109, 0
	v_mov_b32_e32 v110, 0
	v_mov_b32_e32 v111, 0
	v_mov_b32_e32 v112, 0
	v_mov_b32_e32 v113, 0
	v_mov_b32_e32 v114, 0
	v_mov_b32_e32 v115, 0
	v_mov_b32_e32 v116, 0
	v_mov_b32_e32 v117, 0
	v_mov_b32_e32 v118, 0
	v_mov_b32_e32 v119, 0
	v_mov_b32_e32 v120, 0
	v_mov_b32_e32 v121, 0
	v_mov_b32_e32 v122, 0
	v_mov_b32_e32 v123, 0
	v_mov_b32_e32 v124, 0
	v_mov_b32_e32 v125, 0
	v_mov_b32_e32 v126, 0
	v_mov_b32_e32 v127, 0
	v_mov_b32_e32 v128, 0
	v_mov_b32_e32 v129, 0
	s_cbranch_scc1 .LBB0_226
	s_barrier
; DI int wave_of(int tid) { return __builtin_amdgcn_readfirstlane(tid >> 6); }
; #define STAGE_A(P, br, kt) do { const char* _g = (const char*)(A + (long)(br) * lda + (long)(kt) * BK); \
;     __builtin_amdgcn_global_load_lds((const unsigned*)(_g + (size_t)offA0), (unsigned*)((char*)(P) + sb0), 16, 0, 0); \
;     __builtin_amdgcn_global_load_lds((const unsigned*)(_g + (size_t)lda * 128 + (size_t)offA0), (unsigned*)((char*)(P) + sb1), 16, 0, 0); } while (0)
; #define STAGE_B(P, br, kt) do { const char* _g = (const char*)(B + (long)(br) * ldb + (long)(kt) * BK); \
;     __builtin_amdgcn_global_load_lds((const unsigned*)(_g + (size_t)offB0), (unsigned*)((char*)(P) + sb0), 16, 0, 0); \
;     __builtin_amdgcn_global_load_lds((const unsigned*)(_g + (size_t)ldb * 128 + (size_t)offB0), (unsigned*)((char*)(P) + sb1), 16, 0, 0); } while (0)
; #define WAIT_V(n) asm volatile("s_waitcnt vmcnt(" #n ")" ::: "memory")
; #define BAR __builtin_amdgcn_s_barrier()
; DI void gemm_core(WVP char* smem, const u16* __restrict__ A, int lda, int ar0, int ar1,
;                   const u16* __restrict__ B, int ldb, int bc0, int K, AccT& acc) {
;     ...
;   const int wid = wave_of(tid), lane = tid & 63, wr = wid >> 2, wc = wid & 3, fr = lane & 15, fq = lane >> 4;
;   const int sb0 = tid * 16, sb1 = sb0 + 8192;
;   int R0, C0; stage_rc(sb0, R0, C0);
;   const unsigned offA0 = (unsigned)(R0 * lda + C0) * 2u, offB0 = (unsigned)(R0 * ldb + C0) * 2u;
;   const int ac0 = ar0, ac1 = ar1, bb0 = bc0, bb1 = bc0 + HALF;
;   bf16x8 At[4][2], B0[2][2], B1[2][2];
;   const int nt = K / BK;
;   __syncthreads();
;   STAGE_B(SB(0, 0), bb0, 0); STAGE_A(SA(0, 0), ac0, 0);
;   STAGE_B(SB(0, 1), bb1, 0); STAGE_A(SA(0, 1), ac1, 0);
;   if (wr == 1) BAR;
;   WAIT_V(4); BAR;
;   STAGE_B(SB(1, 0), bb0, 1); STAGE_A(SA(1, 0), ac0, 1); STAGE_B(SB(1, 1), bb1, 1);
;   WAIT_V(6); BAR;
.LBB0_226:
	v_add_u32_e32 v141, s61, v8
	v_lshl_add_u64 v[10:11], s[22:23], 0, v[0:1]
	s_ashr_i32 s47, s1, 6
	v_readfirstlane_b32 s1, v141
	v_add_u32_e32 v142, 0x2000, v141
	v_lshl_add_u64 v[10:11], v[10:11], 0, s[64:65]
	s_mov_b32 m0, s1
	v_readfirstlane_b32 s1, v142
	v_add_u32_e32 v143, 0x8000, v136
	s_waitcnt vmcnt(4)
	s_barrier
	global_load_lds_dwordx4 v[10:11], off
	v_lshl_add_u64 v[10:11], s[36:37], 0, v[0:1]
	s_mov_b32 m0, s1
	v_readfirstlane_b32 s1, v143
	v_add_u32_e32 v145, 0xa000, v136
	global_load_lds_dwordx4 v[10:11], off
	v_lshl_add_u64 v[10:11], v[2:3], 0, s[64:65]
	s_mov_b32 m0, s1
	v_readfirstlane_b32 s1, v145
	v_add_u32_e32 v146, s84, v8
	v_lshl_add_u64 v[12:13], s[28:29], 0, v[0:1]
	global_load_lds_dwordx4 v[10:11], off
	v_lshl_add_u64 v[2:3], v[2:3], 0, s[78:79]
	s_mov_b32 m0, s1
	v_readfirstlane_b32 s1, v146
	v_add_u32_e32 v147, 0x2000, v146
	global_load_lds_dwordx4 v[2:3], off
	v_lshl_add_u64 v[2:3], v[12:13], 0, s[64:65]
	s_mov_b32 m0, s1
	v_readfirstlane_b32 s1, v147
	global_load_lds_dwordx4 v[2:3], off
	v_lshl_add_u64 v[2:3], s[38:39], 0, v[0:1]
	s_mov_b32 m0, s1
	v_and_b32_e32 v9, 15, v5
	global_load_lds_dwordx4 v[2:3], off
	v_lshlrev_b32_e32 v2, 2, v5
	v_and_b32_e32 v14, 48, v5
	v_lshlrev_b32_e32 v0, 6, v9
	v_and_b32_e32 v2, 32, v2
	v_bitop3_b32 v0, v0, v2, v14 bitop3:0x36
	v_add_u32_e32 v3, s5, v0
	v_add_u32_e32 v8, s60, v0
	v_add_u32_e32 v9, s61, v0
	v_add_u32_e32 v10, s84, v0
	v_add_u32_e32 v11, 0, v0
	v_lshlrev_b32_e32 v0, 6, v5
	v_and_or_b32 v0, v0, s74, v14
	v_xad_u32 v148, v0, v2, 0
	v_lshlrev_b32_e32 v0, 14, v4
	v_and_b32_e32 v0, 0xffff8000, v0
	s_waitcnt vmcnt(6)
	s_lshl_b32 s1, s47, 12
	v_lshl_add_u32 v0, v6, 11, v0
	v_and_b32_e32 v2, 1, v4
	s_and_b32 s52, s1, 0x3000
	s_lshl_b32 s53, s0, 13
	v_lshl_or_b32 v0, v2, 6, v0
	v_mov_b32_e32 v2, 0
	s_or_b32 s0, s53, 0x800
	s_or_b32 s1, s53, 0x1000
	s_or_b32 s50, s53, 0x1800
	v_lshl_add_u32 v0, v7, 1, v0
	s_mov_b32 s57, -2
	v_add_u32_e32 v149, s52, v3
	v_add_u32_e32 v132, s53, v11
	v_add_u32_e32 v144, s52, v8
	v_add_u32_e32 v135, s52, v9
	v_add_u32_e32 v133, s52, v10
	s_mov_b64 s[52:53], s[42:43]
	s_mov_b64 vcc, s[40:41]
	v_mov_b32_e32 v3, v2
	v_mov_b32_e32 v4, v2
	v_mov_b32_e32 v5, v2
	v_mov_b32_e32 v6, v2
	v_mov_b32_e32 v7, v2
	v_mov_b32_e32 v8, v2
	v_mov_b32_e32 v9, v2
	v_mov_b32_e32 v10, v2
	v_mov_b32_e32 v11, v2
	v_mov_b32_e32 v12, v2
	v_mov_b32_e32 v13, v2
	v_mov_b32_e32 v14, v2
	v_mov_b32_e32 v15, v2
	s_barrier

; DI int get_tid(int wv) { int l; asm volatile("v_mbcnt_lo_u32_b32 %0, -1, 0\n\tv_mbcnt_hi_u32_b32 %0, -1, %0" : "=v"(l)); return wv * 64 + l; }
; DI int wave_of(int tid) { return __builtin_amdgcn_readfirstlane(tid >> 6); }
; #define STAGE_A(P, br, kt) do { const char* _g = (const char*)(A + (long)(br) * lda + (long)(kt) * BK); \
;     __builtin_amdgcn_global_load_lds((const unsigned*)(_g + (size_t)offA0), (unsigned*)((char*)(P) + sb0), 16, 0, 0); \
;     __builtin_amdgcn_global_load_lds((const unsigned*)(_g + (size_t)lda * 128 + (size_t)offA0), (unsigned*)((char*)(P) + sb1), 16, 0, 0); } while (0)
; #define STAGE_B(P, br, kt) do { const char* _g = (const char*)(B + (long)(br) * ldb + (long)(kt) * BK); \
;     __builtin_amdgcn_global_load_lds((const unsigned*)(_g + (size_t)offB0), (unsigned*)((char*)(P) + sb0), 16, 0, 0); \
;     __builtin_amdgcn_global_load_lds((const unsigned*)(_g + (size_t)ldb * 128 + (size_t)offB0), (unsigned*)((char*)(P) + sb1), 16, 0, 0); } while (0)
; #define BAR __builtin_amdgcn_s_barrier()
; DI void gemm_core(WVP char* smem, const u16* __restrict__ A, int lda, int ar0, int ar1,
;                   const u16* __restrict__ B, int ldb, int bc0, int K, AccT& acc) {
;     ...
;   const int tid = get_tid(WV);
;   const int wid = wave_of(tid), lane = tid & 63, wr = wid >> 2, wc = wid & 3, fr = lane & 15, fq = lane >> 4;
;   const int sb0 = tid * 16, sb1 = sb0 + 8192;
;   int R0, C0; stage_rc(sb0, R0, C0);
;   const unsigned offA0 = (unsigned)(R0 * lda + C0) * 2u, offB0 = (unsigned)(R0 * ldb + C0) * 2u;
;   const int ac0 = ar0, ac1 = ar1, bb0 = bc0, bb1 = bc0 + HALF;
;   bf16x8 At[4][2], B0[2][2], B1[2][2];
;   const int nt = K / BK;
;   __syncthreads();
;   STAGE_B(SB(0, 0), bb0, 0); STAGE_A(SA(0, 0), ac0, 0);
;   STAGE_B(SB(0, 1), bb1, 0); STAGE_A(SA(0, 1), ac1, 0);
;   if (wr == 1) BAR;
.LBB0_270:
	s_add_i32 s0, s1, s8
	s_ashr_i32 s1, s0, 31
	v_mbcnt_lo_u32_b32 v7, -1, 0
	v_mbcnt_hi_u32_b32 v7, -1, v7
	s_lshr_b32 s1, s1, 23
	v_add_u32_e32 v0, s3, v7
	v_ashrrev_i32_e32 v2, 31, v0
	s_add_i32 s1, s0, s1
	v_lshrrev_b32_e32 v2, 26, v2
	s_and_b32 s1, s1, 0xfffffe00
	v_readfirstlane_b32 s18, v0
	v_lshlrev_b32_e32 v11, 4, v0
	v_add_u32_e32 v2, v0, v2
	v_bfe_i32 v0, v0, 27, 1
	s_sub_i32 s0, s0, s1
	v_lshrrev_b32_e32 v0, 22, v0
	s_sext_i32_i16 s8, s0
	v_add_u32_e32 v0, v11, v0
	s_bfe_u32 s8, s8, 0x2001d
	v_and_b32_e32 v0, 0xfffffc00, v0
	s_add_i32 s8, s0, s8
	v_sub_u32_e32 v0, v11, v0
	s_sext_i32_i16 s9, s8
	s_and_b32 s8, s8, 0xfffc
	v_ashrrev_i32_e32 v6, 6, v2
	v_lshrrev_b32_e32 v2, 4, v0
	s_sub_i32 s0, s0, s8
	v_bitop3_b32 v0, v2, v0, 32 bitop3:0x6c
	s_sext_i32_i16 s0, s0
	v_ashrrev_i32_e32 v3, 31, v0
	s_ashr_i32 s17, s9, 2
	s_lshl_b32 s0, s0, 7
	v_lshrrev_b32_e32 v3, 26, v3
	s_add_i32 s8, s0, s1
	v_lshlrev_b32_e32 v2, 3, v6
	v_add_u32_e32 v3, v0, v3
	s_mul_i32 s10, s17, 0x260000
	s_add_i32 s14, s8, 0x200
	s_ashr_i32 s0, s18, 8
	v_and_b32_e32 v2, -16, v2
	v_ashrrev_i32_e32 v8, 6, v3
	v_and_b32_e32 v3, 0xc0, v3
	s_ashr_i32 s11, s10, 31
	v_add_u32_e32 v2, v8, v2
	v_sub_u32_e32 v0, v0, v3
	s_movk_i32 s1, 0x1300
	s_add_u32 s12, s4, s10
	v_lshlrev_b32_e32 v4, 5, v6
	v_ashrrev_i16_sdwa v0, v254, sext(v0) dst_sel:DWORD dst_unused:UNUSED_PAD src0_sel:DWORD src1_sel:BYTE_0
	v_lshlrev_b32_e32 v3, 10, v2
	v_mul_lo_u32 v2, v2, s1
	s_addc_u32 s13, s5, s11
	s_add_i32 s1, 0, 0x10000
	v_and_b32_e32 v10, 32, v4
	v_bfe_i32 v9, v0, 0, 16
	v_add_u32_e32 v138, s1, v11
	v_add_u32_e32 v0, v10, v9
	v_readfirstlane_b32 s9, v138
	v_add_u32_e32 v16, 0x2000, v11
	v_lshl_add_u32 v12, v0, 1, v3
	v_add_lshl_u32 v0, v0, v2, 1
	s_mov_b32 m0, s9
	s_barrier
	v_lshl_add_u64 v[2:3], s[12:13], 0, v[0:1]
	global_load_lds_dwordx4 v0, s[12:13]
	v_add_u32_e32 v0, s1, v16
	s_mov_b64 s[12:13], 0x98000
	v_readfirstlane_b32 s9, v0
	s_mov_b32 m0, s9
	s_ashr_i32 s9, s8, 31
	v_lshl_add_u64 v[4:5], v[2:3], 0, s[12:13]
	s_lshl_b64 s[12:13], s[8:9], 10
	v_readlane_b32 s19, v255, 43
	s_add_u32 s20, s19, s12
	v_readlane_b32 s24, v255, 44
	v_add_u32_e32 v140, 0, v11
	s_addc_u32 s21, s24, s13
	v_mov_b32_e32 v13, v1
	v_readfirstlane_b32 s15, v140
	v_add_u32_e32 v141, 0x2000, v140
	global_load_lds_dwordx4 v[4:5], off
	v_lshl_add_u64 v[4:5], s[20:21], 0, v[12:13]
	s_mov_b32 m0, s15
	s_mov_b64 s[22:23], 0x10000
	v_readfirstlane_b32 s15, v141
	v_add_u32_e32 v143, s60, v11
	global_load_lds_dwordx4 v12, s[20:21]
	v_lshl_add_u64 v[14:15], v[4:5], 0, s[22:23]
	s_mov_b32 m0, s15
	s_mov_b64 s[20:21], 0x130000
	v_readfirstlane_b32 s15, v143
	v_add_u32_e32 v0, s60, v16
	global_load_lds_dwordx4 v[14:15], off
	v_lshl_add_u64 v[14:15], v[2:3], 0, s[20:21]
	s_mov_b32 m0, s15
	v_readfirstlane_b32 s15, v0
	global_load_lds_dwordx4 v[14:15], off
	s_mov_b32 m0, s15
	s_ashr_i32 s15, s14, 31
	s_mov_b64 s[20:21], 0x1c8000
	s_lshl_b64 s[14:15], s[14:15], 10
	v_lshl_add_u64 v[14:15], v[2:3], 0, s[20:21]
	s_add_u32 s20, s19, s14
	v_add_u32_e32 v144, 0x4000, v140
	s_addc_u32 s21, s24, s15
	v_readfirstlane_b32 s19, v144
	v_add_u32_e32 v145, 0x6000, v140
	global_load_lds_dwordx4 v[14:15], off
	v_lshl_add_u64 v[130:131], s[20:21], 0, v[12:13]
	s_mov_b32 m0, s19
	v_readfirstlane_b32 s19, v145
	global_load_lds_dwordx4 v12, s[20:21]
	v_lshl_add_u64 v[12:13], v[130:131], 0, s[22:23]
	s_mov_b32 m0, s19
	s_cmp_lg_u32 s0, 1
	global_load_lds_dwordx4 v[12:13], off
	v_mov_b32_e32 v16, 0
	v_mov_b32_e32 v17, 0
	v_mov_b32_e32 v18, 0
	v_mov_b32_e32 v19, 0
	v_mov_b32_e32 v20, 0
	v_mov_b32_e32 v21, 0
	v_mov_b32_e32 v22, 0
	v_mov_b32_e32 v23, 0
	v_mov_b32_e32 v24, 0
	v_mov_b32_e32 v25, 0
	v_mov_b32_e32 v26, 0
	v_mov_b32_e32 v27, 0
	v_mov_b32_e32 v28, 0
	v_mov_b32_e32 v29, 0
	v_mov_b32_e32 v30, 0
	v_mov_b32_e32 v31, 0
	v_mov_b32_e32 v32, 0
	v_mov_b32_e32 v33, 0
	v_mov_b32_e32 v34, 0
	v_mov_b32_e32 v35, 0
	v_mov_b32_e32 v36, 0
	v_mov_b32_e32 v37, 0
	v_mov_b32_e32 v38, 0
	v_mov_b32_e32 v39, 0
	v_mov_b32_e32 v40, 0
	v_mov_b32_e32 v41, 0
	v_mov_b32_e32 v42, 0
	v_mov_b32_e32 v43, 0
	v_mov_b32_e32 v44, 0
	v_mov_b32_e32 v45, 0
	v_mov_b32_e32 v46, 0
	v_mov_b32_e32 v47, 0
	v_mov_b32_e32 v48, 0
	v_mov_b32_e32 v49, 0
	v_mov_b32_e32 v50, 0
	v_mov_b32_e32 v51, 0
	v_mov_b32_e32 v52, 0
	v_mov_b32_e32 v53, 0
	v_mov_b32_e32 v54, 0
	v_mov_b32_e32 v55, 0
	v_mov_b32_e32 v56, 0
	v_mov_b32_e32 v57, 0
	v_mov_b32_e32 v58, 0
	v_mov_b32_e32 v59, 0
	v_mov_b32_e32 v60, 0
	v_mov_b32_e32 v61, 0
	v_mov_b32_e32 v62, 0
	v_mov_b32_e32 v63, 0
	v_mov_b32_e32 v64, 0
	v_mov_b32_e32 v65, 0
	v_mov_b32_e32 v66, 0
	v_mov_b32_e32 v67, 0
	v_mov_b32_e32 v68, 0
	v_mov_b32_e32 v69, 0
	v_mov_b32_e32 v70, 0
	v_mov_b32_e32 v71, 0
	v_mov_b32_e32 v72, 0
	v_mov_b32_e32 v73, 0
	v_mov_b32_e32 v74, 0
	v_mov_b32_e32 v75, 0
	v_mov_b32_e32 v76, 0
	v_mov_b32_e32 v77, 0
	v_mov_b32_e32 v78, 0
	v_mov_b32_e32 v79, 0
	v_mov_b32_e32 v80, 0
	v_mov_b32_e32 v81, 0
	v_mov_b32_e32 v82, 0
	v_mov_b32_e32 v83, 0
	v_mov_b32_e32 v84, 0
	v_mov_b32_e32 v85, 0
	v_mov_b32_e32 v86, 0
	v_mov_b32_e32 v87, 0
	v_mov_b32_e32 v88, 0
	v_mov_b32_e32 v89, 0
	v_mov_b32_e32 v90, 0
	v_mov_b32_e32 v91, 0
	v_mov_b32_e32 v92, 0
	v_mov_b32_e32 v93, 0
	v_mov_b32_e32 v94, 0
	v_mov_b32_e32 v95, 0
	v_mov_b32_e32 v96, 0
	v_mov_b32_e32 v97, 0
	v_mov_b32_e32 v98, 0
	v_mov_b32_e32 v99, 0
	v_mov_b32_e32 v100, 0
	v_mov_b32_e32 v101, 0
	v_mov_b32_e32 v102, 0
	v_mov_b32_e32 v103, 0
	v_mov_b32_e32 v104, 0
	v_mov_b32_e32 v105, 0
	v_mov_b32_e32 v106, 0
	v_mov_b32_e32 v107, 0
	v_mov_b32_e32 v108, 0
	v_mov_b32_e32 v109, 0
	v_mov_b32_e32 v110, 0
	v_mov_b32_e32 v111, 0
	v_mov_b32_e32 v112, 0
	v_mov_b32_e32 v113, 0
	v_mov_b32_e32 v114, 0
	v_mov_b32_e32 v115, 0
	v_mov_b32_e32 v116, 0
	v_mov_b32_e32 v117, 0
	v_mov_b32_e32 v118, 0
	v_mov_b32_e32 v119, 0
	v_mov_b32_e32 v120, 0
	v_mov_b32_e32 v121, 0
	v_mov_b32_e32 v122, 0
	v_mov_b32_e32 v123, 0
	v_mov_b32_e32 v124, 0
	v_mov_b32_e32 v125, 0
	v_mov_b32_e32 v126, 0
	v_mov_b32_e32 v127, 0
	v_mov_b32_e32 v128, 0
	v_mov_b32_e32 v129, 0
	s_cbranch_scc1 .LBB0_272
	s_barrier
; DI int wave_of(int tid) { return __builtin_amdgcn_readfirstlane(tid >> 6); }
; #define STAGE_A(P, br, kt) do { const char* _g = (const char*)(A + (long)(br) * lda + (long)(kt) * BK); \
;     __builtin_amdgcn_global_load_lds((const unsigned*)(_g + (size_t)offA0), (unsigned*)((char*)(P) + sb0), 16, 0, 0); \
;     __builtin_amdgcn_global_load_lds((const unsigned*)(_g + (size_t)lda * 128 + (size_t)offA0), (unsigned*)((char*)(P) + sb1), 16, 0, 0); } while (0)
; #define STAGE_B(P, br, kt) do { const char* _g = (const char*)(B + (long)(br) * ldb + (long)(kt) * BK); \
;     __builtin_amdgcn_global_load_lds((const unsigned*)(_g + (size_t)offB0), (unsigned*)((char*)(P) + sb0), 16, 0, 0); \
;     __builtin_amdgcn_global_load_lds((const unsigned*)(_g + (size_t)ldb * 128 + (size_t)offB0), (unsigned*)((char*)(P) + sb1), 16, 0, 0); } while (0)
; #define WAIT_V(n) asm volatile("s_waitcnt vmcnt(" #n ")" ::: "memory")
; #define BAR __builtin_amdgcn_s_barrier()
; DI void gemm_core(WVP char* smem, const u16* __restrict__ A, int lda, int ar0, int ar1,
;                   const u16* __restrict__ B, int ldb, int bc0, int K, AccT& acc) {
;     ...
;   const int wid = wave_of(tid), lane = tid & 63, wr = wid >> 2, wc = wid & 3, fr = lane & 15, fq = lane >> 4;
;   const int sb0 = tid * 16, sb1 = sb0 + 8192;
;   int R0, C0; stage_rc(sb0, R0, C0);
;   const unsigned offA0 = (unsigned)(R0 * lda + C0) * 2u, offB0 = (unsigned)(R0 * ldb + C0) * 2u;
;   const int ac0 = ar0, ac1 = ar1, bb0 = bc0, bb1 = bc0 + HALF;
;   bf16x8 At[4][2], B0[2][2], B1[2][2];
;   const int nt = K / BK;
;   __syncthreads();
;   STAGE_B(SB(0, 0), bb0, 0); STAGE_A(SA(0, 0), ac0, 0);
;   STAGE_B(SB(0, 1), bb1, 0); STAGE_A(SA(0, 1), ac1, 0);
;   if (wr == 1) BAR;
;   WAIT_V(4); BAR;
;   STAGE_B(SB(1, 0), bb0, 1); STAGE_A(SA(1, 0), ac0, 1); STAGE_B(SB(1, 1), bb1, 1);
;   WAIT_V(6); BAR;
.LBB0_272:
	v_add_u32_e32 v146, s61, v11
	v_add_u32_e32 v147, 0x2000, v146
	v_readfirstlane_b32 s19, v146
	v_lshl_add_u64 v[12:13], v[2:3], 0, s[64:65]
	s_mov_b32 m0, s19
	s_mov_b64 s[20:21], 0x98080
	v_readfirstlane_b32 s19, v147
	v_add_u32_e32 v148, 0x8000, v140
	s_waitcnt vmcnt(4)
	s_barrier
	global_load_lds_dwordx4 v[12:13], off
	v_lshl_add_u64 v[12:13], v[2:3], 0, s[20:21]
	s_mov_b32 m0, s19
	v_readfirstlane_b32 s19, v148
	v_add_u32_e32 v149, 0xa000, v140
	global_load_lds_dwordx4 v[12:13], off
	v_lshl_add_u64 v[12:13], v[4:5], 0, s[64:65]
	s_mov_b32 m0, s19
	s_mov_b64 s[20:21], 0x10080
	v_readfirstlane_b32 s19, v149
	v_add_u32_e32 v150, s84, v11
	global_load_lds_dwordx4 v[12:13], off
	v_lshl_add_u64 v[4:5], v[4:5], 0, s[20:21]
	s_mov_b32 m0, s19
	s_mov_b64 s[20:21], 0x130080
	v_readfirstlane_b32 s19, v150
	v_add_u32_e32 v152, 0x2000, v150
	global_load_lds_dwordx4 v[4:5], off
	v_lshl_add_u64 v[4:5], v[2:3], 0, s[20:21]
	s_mov_b32 m0, s19
	s_mov_b64 s[20:21], 0x1c8080
	v_readfirstlane_b32 s19, v152
	global_load_lds_dwordx4 v[4:5], off
	v_lshl_add_u64 v[2:3], v[2:3], 0, s[20:21]
	s_mov_b32 m0, s19
	v_and_b32_e32 v0, 15, v7
	global_load_lds_dwordx4 v[2:3], off
	v_lshlrev_b32_e32 v2, 2, v7
	v_and_b32_e32 v14, 48, v7
	v_lshlrev_b32_e32 v0, 6, v0
	v_and_b32_e32 v2, 32, v2
	v_bitop3_b32 v0, v0, v2, v14 bitop3:0x36
	v_add_u32_e32 v4, s1, v0
	v_add_u32_e32 v5, s60, v0
	v_add_u32_e32 v11, s61, v0
	v_add_u32_e32 v12, s84, v0
	v_add_u32_e32 v13, 0, v0
	v_lshlrev_b32_e32 v0, 6, v7
	v_and_or_b32 v0, v0, s74, v14
	s_movk_i32 s20, 0x1300
	v_xad_u32 v153, v0, v2, 0
	v_lshrrev_b32_e32 v7, 1, v6
	v_mul_lo_u32 v0, v8, s20
	s_mov_b32 s20, 0x13000
	v_mad_u64_u32 v[2:3], s[20:21], v7, s20, v[0:1]
	v_or_b32_e32 v0, v2, v10
	v_add_lshl_u32 v0, v0, v9, 1
	v_lshl_add_u64 v[132:133], s[10:11], 0, v[0:1]
	v_lshlrev_b32_e32 v0, 10, v8
	s_ashr_i32 s18, s18, 6
	v_lshl_add_u32 v0, v7, 14, v0
	v_and_b32_e32 v2, 1, v6
	s_waitcnt vmcnt(6)
	s_lshl_b32 s19, s18, 12
	v_lshl_or_b32 v0, v2, 6, v0
	s_and_b32 s22, s19, 0x3000
	s_lshl_b32 s23, s0, 13
	v_lshl_add_u32 v0, v9, 1, v0
	v_mov_b32_e32 v2, 0
	s_or_b32 s0, s23, 0x800
	s_or_b32 s1, s23, 0x1000
	s_or_b32 s19, s23, 0x1800
	v_lshl_add_u64 v[134:135], s[12:13], 0, v[0:1]
	v_lshl_add_u64 v[136:137], s[14:15], 0, v[0:1]
	s_mov_b32 s12, -2
	v_add_u32_e32 v154, s22, v4
	v_add_u32_e32 v0, s23, v13
	v_add_u32_e32 v151, s22, v5
	v_add_u32_e32 v142, s22, v11
	v_add_u32_e32 v139, s22, v12
	s_mov_b64 s[10:11], s[54:55]
	v_mov_b32_e32 v3, v2
	v_mov_b32_e32 v4, v2
	v_mov_b32_e32 v5, v2
	v_mov_b32_e32 v6, v2
	v_mov_b32_e32 v7, v2
	v_mov_b32_e32 v8, v2
	v_mov_b32_e32 v9, v2
	v_mov_b32_e32 v10, v2
	v_mov_b32_e32 v11, v2
	v_mov_b32_e32 v12, v2
	v_mov_b32_e32 v13, v2
	v_mov_b32_e32 v14, v2
	v_mov_b32_e32 v15, v2
	s_mov_b64 s[20:21], 0x1f900100
	s_mov_b64 s[22:23], 0x1f910100
	s_barrier

; DI int get_tid(int wv) { int l; asm volatile("v_mbcnt_lo_u32_b32 %0, -1, 0\n\tv_mbcnt_hi_u32_b32 %0, -1, %0" : "=v"(l)); return wv * 64 + l; }
; DI int wave_of(int tid) { return __builtin_amdgcn_readfirstlane(tid >> 6); }
; #define STAGE_A(P, br, kt) do { const char* _g = (const char*)(A + (long)(br) * lda + (long)(kt) * BK); \
;     __builtin_amdgcn_global_load_lds((const unsigned*)(_g + (size_t)offA0), (unsigned*)((char*)(P) + sb0), 16, 0, 0); \
;     __builtin_amdgcn_global_load_lds((const unsigned*)(_g + (size_t)lda * 128 + (size_t)offA0), (unsigned*)((char*)(P) + sb1), 16, 0, 0); } while (0)
; #define STAGE_B(P, br, kt) do { const char* _g = (const char*)(B + (long)(br) * ldb + (long)(kt) * BK); \
;     __builtin_amdgcn_global_load_lds((const unsigned*)(_g + (size_t)offB0), (unsigned*)((char*)(P) + sb0), 16, 0, 0); \
;     __builtin_amdgcn_global_load_lds((const unsigned*)(_g + (size_t)ldb * 128 + (size_t)offB0), (unsigned*)((char*)(P) + sb1), 16, 0, 0); } while (0)
; #define BAR __builtin_amdgcn_s_barrier()
; DI void gemm_core(WVP char* smem, const u16* __restrict__ A, int lda, int ar0, int ar1,
;                   const u16* __restrict__ B, int ldb, int bc0, int K, AccT& acc) {
;     ...
;   const int tid = get_tid(WV);
;   const int wid = wave_of(tid), lane = tid & 63, wr = wid >> 2, wc = wid & 3, fr = lane & 15, fq = lane >> 4;
;   const int sb0 = tid * 16, sb1 = sb0 + 8192;
;   int R0, C0; stage_rc(sb0, R0, C0);
;   const unsigned offA0 = (unsigned)(R0 * lda + C0) * 2u, offB0 = (unsigned)(R0 * ldb + C0) * 2u;
;   const int ac0 = ar0, ac1 = ar1, bb0 = bc0, bb1 = bc0 + HALF;
;   bf16x8 At[4][2], B0[2][2], B1[2][2];
;   const int nt = K / BK;
;   __syncthreads();
;   STAGE_B(SB(0, 0), bb0, 0); STAGE_A(SA(0, 0), ac0, 0);
;   STAGE_B(SB(0, 1), bb1, 0); STAGE_A(SA(0, 1), ac1, 0);
;   if (wr == 1) BAR;
.LBB0_424:
	s_ashr_i32 s0, s4, 31
	s_lshr_b32 s0, s0, 29
	s_add_i32 s0, s4, s0
	s_ashr_i32 s1, s0, 3
	s_and_b32 s0, s0, -8
	s_sub_i32 s0, s4, s0
	s_mov_b32 s26, s4
	s_cmp_lt_i32 s0, 0
	s_movk_i32 s4, 0x131
	s_cselect_b32 s4, s4, 0x130
	s_mul_i32 s14, s0, s4
	s_add_i32 s14, s14, s1
	s_ashr_i32 s0, s14, 31
	s_lshr_b32 s0, s0, 23
	s_add_i32 s0, s14, s0
	s_ashr_i32 s15, s0, 9
	s_lshl_b32 s4, s15, 2
	s_sub_i32 s1, 19, s4
	s_min_u32 s5, s1, 4
	s_and_b32 s0, s0, 0xfffffe00
	s_sub_i32 s8, s14, s0
	v_cvt_f32_ubyte0_e32 v2, s5
	v_cvt_f32_i32_e32 v0, s8
	v_rcp_iflag_f32_e32 v3, v2
	s_ashr_i32 s0, s8, 30
	s_or_b32 s9, s0, 1
	v_mbcnt_lo_u32_b32 v9, -1, 0
	v_mbcnt_hi_u32_b32 v9, -1, v9
	v_mul_f32_e32 v3, v0, v3
	v_trunc_f32_e32 v3, v3
	v_fma_f32 v0, -v3, v2, v0
	v_cvt_i32_f32_e32 v3, v3
	v_cmp_ge_f32_e64 s[0:1], |v0|, v2
	s_and_b64 s[0:1], s[0:1], exec
	s_cselect_b32 s0, s9, 0
	v_readfirstlane_b32 s1, v3
	s_add_i32 s16, s1, s0
	s_sext_i32_i16 s0, s16
	s_mul_i32 s16, s16, s5
	v_add_u32_e32 v0, s3, v9
	s_sub_i32 s1, s8, s16
	v_ashrrev_i32_e32 v2, 31, v0
	s_sext_i32_i16 s1, s1
	v_lshrrev_b32_e32 v2, 26, v2
	s_add_i32 s4, s4, s1
	v_readfirstlane_b32 s1, v0
	v_lshlrev_b32_e32 v12, 4, v0
	v_add_u32_e32 v2, v0, v2
	v_bfe_i32 v0, v0, 27, 1
	v_lshrrev_b32_e32 v0, 22, v0
	v_add_u32_e32 v0, v12, v0
	v_and_b32_e32 v0, 0xfffffc00, v0
	v_sub_u32_e32 v0, v12, v0
	v_ashrrev_i32_e32 v8, 6, v2
	v_lshrrev_b32_e32 v2, 4, v0
	v_bitop3_b32 v0, v2, v0, 32 bitop3:0x6c
	v_ashrrev_i32_e32 v3, 31, v0
	s_lshl_b32 s10, s0, 8
	v_lshrrev_b32_e32 v3, 26, v3
	s_lshl_b32 s8, s4, 8
	v_add_u32_e32 v3, v0, v3
	s_ashr_i32 s11, s10, 31
	s_or_b32 s18, s8, 0x80
	s_ashr_i32 s0, s1, 8
	v_ashrrev_i32_e32 v10, 6, v3
	v_and_b32_e32 v3, 0xc0, v3
	s_or_b32 s20, s10, 0x80
	s_lshl_b64 s[12:13], s[10:11], 11
	v_readlane_b32 s28, v255, 29
	v_sub_u32_e32 v0, v0, v3
	v_readlane_b32 s29, v255, 30
	s_add_u32 s22, s28, s12
	v_lshlrev_b32_e32 v2, 3, v8
	v_lshlrev_b32_e32 v4, 5, v8
	v_ashrrev_i16_sdwa v0, v254, sext(v0) dst_sel:DWORD dst_unused:UNUSED_PAD src0_sel:DWORD src1_sel:BYTE_0
	s_addc_u32 s23, s29, s13
	s_add_i32 s5, 0, 0x10000
	v_and_b32_e32 v2, 0x1ffff0, v2
	v_and_b32_e32 v4, 32, v4
	v_bfe_i32 v11, v0, 0, 16
	v_add_u32_e32 v133, s5, v12
	v_add_u32_e32 v0, v4, v11
	v_add_lshl_u32 v2, v10, v2, 11
	v_readfirstlane_b32 s4, v133
	v_lshl_add_u32 v0, v0, 1, v2
	s_mov_b32 m0, s4
	s_ashr_i32 s9, s8, 31
	s_barrier
	v_lshl_add_u64 v[2:3], s[22:23], 0, v[0:1]
	global_load_lds_dwordx4 v0, s[22:23]
	s_lshl_b64 s[22:23], s[8:9], 11
	v_add_u32_e32 v13, 0x2000, v12
	s_add_u32 s22, s24, s22
	v_add_u32_e32 v6, s5, v13
	s_addc_u32 s23, s25, s23
	s_ashr_i32 s21, s20, 31
	v_readfirstlane_b32 s4, v6
	v_add_u32_e32 v135, 0, v12
	s_lshl_b64 s[20:21], s[20:21], 11
	v_lshl_add_u64 v[4:5], v[2:3], 0, s[76:77]
	s_mov_b32 m0, s4
	v_readfirstlane_b32 s4, v135
	v_add_u32_e32 v136, 0x2000, v135
	s_add_u32 s20, s28, s20
	global_load_lds_dwordx4 v[4:5], off
	v_lshl_add_u64 v[4:5], s[22:23], 0, v[0:1]
	s_mov_b32 m0, s4
	v_readfirstlane_b32 s4, v136
	s_addc_u32 s21, s29, s21
	v_add_u32_e32 v137, s60, v12
	s_ashr_i32 s19, s18, 31
	global_load_lds_dwordx4 v0, s[22:23]
	v_lshl_add_u64 v[6:7], v[4:5], 0, s[76:77]
	s_mov_b32 m0, s4
	v_readfirstlane_b32 s4, v137
	v_add_u32_e32 v13, s60, v13
	s_lshl_b64 s[18:19], s[18:19], 11
	global_load_lds_dwordx4 v[6:7], off
	v_lshl_add_u64 v[6:7], s[20:21], 0, v[0:1]
	s_mov_b32 m0, s4
	v_readfirstlane_b32 s4, v13
	s_add_u32 s18, s24, s18
	v_add_u32_e32 v139, 0x4000, v135
	global_load_lds_dwordx4 v0, s[20:21]
	v_lshl_add_u64 v[14:15], v[6:7], 0, s[76:77]
	s_mov_b32 m0, s4
	s_addc_u32 s19, s25, s19
	v_readfirstlane_b32 s4, v139
	v_add_u32_e32 v140, 0x6000, v135
	global_load_lds_dwordx4 v[14:15], off
	v_lshl_add_u64 v[130:131], s[18:19], 0, v[0:1]
	s_mov_b32 m0, s4
	v_readfirstlane_b32 s4, v140
	global_load_lds_dwordx4 v0, s[18:19]
	v_lshl_add_u64 v[14:15], v[130:131], 0, s[76:77]
	s_mov_b32 m0, s4
	s_cmp_lg_u32 s0, 1
	global_load_lds_dwordx4 v[14:15], off
	v_mov_b32_e32 v16, 0
	v_mov_b32_e32 v17, 0
	v_mov_b32_e32 v18, 0
	v_mov_b32_e32 v19, 0
	v_mov_b32_e32 v20, 0
	v_mov_b32_e32 v21, 0
	v_mov_b32_e32 v22, 0
	v_mov_b32_e32 v23, 0
	v_mov_b32_e32 v24, 0
	v_mov_b32_e32 v25, 0
	v_mov_b32_e32 v26, 0
	v_mov_b32_e32 v27, 0
	v_mov_b32_e32 v28, 0
	v_mov_b32_e32 v29, 0
	v_mov_b32_e32 v30, 0
	v_mov_b32_e32 v31, 0
	v_mov_b32_e32 v32, 0
	v_mov_b32_e32 v33, 0
	v_mov_b32_e32 v34, 0
	v_mov_b32_e32 v35, 0
	v_mov_b32_e32 v36, 0
	v_mov_b32_e32 v37, 0
	v_mov_b32_e32 v38, 0
	v_mov_b32_e32 v39, 0
	v_mov_b32_e32 v40, 0
	v_mov_b32_e32 v41, 0
	v_mov_b32_e32 v42, 0
	v_mov_b32_e32 v43, 0
	v_mov_b32_e32 v44, 0
	v_mov_b32_e32 v45, 0
	v_mov_b32_e32 v46, 0
	v_mov_b32_e32 v47, 0
	v_mov_b32_e32 v48, 0
	v_mov_b32_e32 v49, 0
	v_mov_b32_e32 v50, 0
	v_mov_b32_e32 v51, 0
	v_mov_b32_e32 v52, 0
	v_mov_b32_e32 v53, 0
	v_mov_b32_e32 v54, 0
	v_mov_b32_e32 v55, 0
	v_mov_b32_e32 v56, 0
	v_mov_b32_e32 v57, 0
	v_mov_b32_e32 v58, 0
	v_mov_b32_e32 v59, 0
	v_mov_b32_e32 v60, 0
	v_mov_b32_e32 v61, 0
	v_mov_b32_e32 v62, 0
	v_mov_b32_e32 v63, 0
	v_mov_b32_e32 v64, 0
	v_mov_b32_e32 v65, 0
	v_mov_b32_e32 v66, 0
	v_mov_b32_e32 v67, 0
	v_mov_b32_e32 v68, 0
	v_mov_b32_e32 v69, 0
	v_mov_b32_e32 v70, 0
	v_mov_b32_e32 v71, 0
	v_mov_b32_e32 v72, 0
	v_mov_b32_e32 v73, 0
	v_mov_b32_e32 v74, 0
	v_mov_b32_e32 v75, 0
	v_mov_b32_e32 v76, 0
	v_mov_b32_e32 v77, 0
	v_mov_b32_e32 v78, 0
	v_mov_b32_e32 v79, 0
	v_mov_b32_e32 v80, 0
	v_mov_b32_e32 v81, 0
	v_mov_b32_e32 v82, 0
	v_mov_b32_e32 v83, 0
	v_mov_b32_e32 v84, 0
	v_mov_b32_e32 v85, 0
	v_mov_b32_e32 v86, 0
	v_mov_b32_e32 v87, 0
	v_mov_b32_e32 v88, 0
	v_mov_b32_e32 v89, 0
	v_mov_b32_e32 v90, 0
	v_mov_b32_e32 v91, 0
	v_mov_b32_e32 v92, 0
	v_mov_b32_e32 v93, 0
	v_mov_b32_e32 v94, 0
	v_mov_b32_e32 v95, 0
	v_mov_b32_e32 v96, 0
	v_mov_b32_e32 v97, 0
	v_mov_b32_e32 v98, 0
	v_mov_b32_e32 v99, 0
	v_mov_b32_e32 v100, 0
	v_mov_b32_e32 v101, 0
	v_mov_b32_e32 v102, 0
	v_mov_b32_e32 v103, 0
	v_mov_b32_e32 v104, 0
	v_mov_b32_e32 v105, 0
	v_mov_b32_e32 v106, 0
	v_mov_b32_e32 v107, 0
	v_mov_b32_e32 v108, 0
	v_mov_b32_e32 v109, 0
	v_mov_b32_e32 v110, 0
	v_mov_b32_e32 v111, 0
	v_mov_b32_e32 v112, 0
	v_mov_b32_e32 v113, 0
	v_mov_b32_e32 v114, 0
	v_mov_b32_e32 v115, 0
	v_mov_b32_e32 v116, 0
	v_mov_b32_e32 v117, 0
	v_mov_b32_e32 v118, 0
	v_mov_b32_e32 v119, 0
	v_mov_b32_e32 v120, 0
	v_mov_b32_e32 v121, 0
	v_mov_b32_e32 v122, 0
	v_mov_b32_e32 v123, 0
	v_mov_b32_e32 v124, 0
	v_mov_b32_e32 v125, 0
	v_mov_b32_e32 v126, 0
	v_mov_b32_e32 v127, 0
	v_mov_b32_e32 v128, 0
	v_mov_b32_e32 v129, 0
	s_cbranch_scc1 .LBB0_426
	s_barrier
; DI int wave_of(int tid) { return __builtin_amdgcn_readfirstlane(tid >> 6); }
; #define STAGE_A(P, br, kt) do { const char* _g = (const char*)(A + (long)(br) * lda + (long)(kt) * BK); \
;     __builtin_amdgcn_global_load_lds((const unsigned*)(_g + (size_t)offA0), (unsigned*)((char*)(P) + sb0), 16, 0, 0); \
;     __builtin_amdgcn_global_load_lds((const unsigned*)(_g + (size_t)lda * 128 + (size_t)offA0), (unsigned*)((char*)(P) + sb1), 16, 0, 0); } while (0)
; #define STAGE_B(P, br, kt) do { const char* _g = (const char*)(B + (long)(br) * ldb + (long)(kt) * BK); \
;     __builtin_amdgcn_global_load_lds((const unsigned*)(_g + (size_t)offB0), (unsigned*)((char*)(P) + sb0), 16, 0, 0); \
;     __builtin_amdgcn_global_load_lds((const unsigned*)(_g + (size_t)ldb * 128 + (size_t)offB0), (unsigned*)((char*)(P) + sb1), 16, 0, 0); } while (0)
; #define WAIT_V(n) asm volatile("s_waitcnt vmcnt(" #n ")" ::: "memory")
; #define BAR __builtin_amdgcn_s_barrier()
; DI void gemm_core(WVP char* smem, const u16* __restrict__ A, int lda, int ar0, int ar1,
;                   const u16* __restrict__ B, int ldb, int bc0, int K, AccT& acc) {
;     ...
;   const int wid = wave_of(tid), lane = tid & 63, wr = wid >> 2, wc = wid & 3, fr = lane & 15, fq = lane >> 4;
;   const int sb0 = tid * 16, sb1 = sb0 + 8192;
;   int R0, C0; stage_rc(sb0, R0, C0);
;   const unsigned offA0 = (unsigned)(R0 * lda + C0) * 2u, offB0 = (unsigned)(R0 * ldb + C0) * 2u;
;   const int ac0 = ar0, ac1 = ar1, bb0 = bc0, bb1 = bc0 + HALF;
;   bf16x8 At[4][2], B0[2][2], B1[2][2];
;   const int nt = K / BK;
;   __syncthreads();
;   STAGE_B(SB(0, 0), bb0, 0); STAGE_A(SA(0, 0), ac0, 0);
;   STAGE_B(SB(0, 1), bb1, 0); STAGE_A(SA(0, 1), ac1, 0);
;   if (wr == 1) BAR;
;   WAIT_V(4); BAR;
;   STAGE_B(SB(1, 0), bb0, 1); STAGE_A(SA(1, 0), ac0, 1); STAGE_B(SB(1, 1), bb1, 1);
;   WAIT_V(6); BAR;
.LBB0_426:
	v_add_u32_e32 v141, s61, v12
	s_ashr_i32 s4, s1, 6
	v_readfirstlane_b32 s1, v141
	v_add_u32_e32 v142, 0x2000, v141
	v_lshl_add_u64 v[14:15], v[2:3], 0, s[64:65]
	s_mov_b32 m0, s1
	v_readfirstlane_b32 s1, v142
	v_add_u32_e32 v143, 0x8000, v135
	s_waitcnt vmcnt(4)
	s_barrier
	global_load_lds_dwordx4 v[14:15], off
	v_lshl_add_u64 v[2:3], v[2:3], 0, s[78:79]
	s_mov_b32 m0, s1
	v_readfirstlane_b32 s1, v143
	v_add_u32_e32 v144, 0xa000, v135
	global_load_lds_dwordx4 v[2:3], off
	v_lshl_add_u64 v[2:3], v[4:5], 0, s[64:65]
	s_mov_b32 m0, s1
	v_readfirstlane_b32 s1, v144
	v_add_u32_e32 v145, s84, v12
	global_load_lds_dwordx4 v[2:3], off
	v_lshl_add_u64 v[2:3], v[4:5], 0, s[78:79]
	s_mov_b32 m0, s1
	v_readfirstlane_b32 s1, v145
	v_add_u32_e32 v146, 0x2000, v145
	global_load_lds_dwordx4 v[2:3], off
	v_lshl_add_u64 v[2:3], v[6:7], 0, s[64:65]
	s_mov_b32 m0, s1
	v_readfirstlane_b32 s1, v146
	global_load_lds_dwordx4 v[2:3], off
	v_lshl_add_u64 v[2:3], v[6:7], 0, s[78:79]
	s_mov_b32 m0, s1
	v_and_b32_e32 v0, 15, v9
	global_load_lds_dwordx4 v[2:3], off
	v_lshlrev_b32_e32 v2, 2, v9
	v_and_b32_e32 v13, 48, v9
	v_lshlrev_b32_e32 v0, 6, v0
	v_and_b32_e32 v2, 32, v2
	s_lshl_b32 s1, s4, 12
	v_bitop3_b32 v0, v0, v2, v13 bitop3:0x36
	s_lshl_b32 s17, s0, 13
	s_and_b32 s11, s1, 0x3000
	v_add_u32_e32 v3, s5, v0
	s_or_b32 s0, s17, 0x800
	s_or_b32 s1, s17, 0x1000
	s_or_b32 s5, s17, 0x1800
	s_add_u32 s12, s54, s12
	s_addc_u32 s13, s55, s13
	s_lshl_b32 s9, s15, 10
	s_sub_i32 s14, s14, s16
	s_lshl_b32 s15, s15, 9
	s_sub_i32 s14, s14, s15
	v_add_u32_e32 v4, s60, v0
	v_add_u32_e32 v5, s61, v0
	v_add_u32_e32 v6, s84, v0
	v_add_u32_e32 v7, 0, v0
	v_lshlrev_b32_e32 v0, 6, v9
	s_sext_i32_i16 s14, s14
	v_and_or_b32 v0, v0, s74, v13
	s_lshl_b32 s14, s14, 8
	v_xad_u32 v148, v0, v2, 0
	v_lshlrev_b32_e32 v0, 14, v8
	s_add_i32 s14, s9, s14
	v_and_b32_e32 v0, 0xffff8000, v0
	s_ashr_i32 s15, s14, 31
	s_waitcnt vmcnt(6)
	v_lshl_add_u32 v0, v10, 11, v0
	v_and_b32_e32 v2, 1, v8
	s_lshl_b64 s[14:15], s[14:15], 11
	v_lshl_or_b32 v0, v2, 6, v0
	s_add_u32 s14, s54, s14
	v_mov_b32_e32 v2, 0
	v_mov_b32_e32 v205, 0x358637bd
	v_lshl_add_u32 v0, v11, 1, v0
	s_addc_u32 s15, s55, s15
	s_mov_b32 s9, -2
	v_add_u32_e32 v149, s11, v3
	v_add_u32_e32 v132, s17, v7
	v_add_u32_e32 v147, s11, v4
	v_add_u32_e32 v138, s11, v5
	v_add_u32_e32 v134, s11, v6
	v_mov_b32_e32 v3, v2
	v_mov_b32_e32 v4, v2
	v_mov_b32_e32 v5, v2
	v_mov_b32_e32 v6, v2
	v_mov_b32_e32 v7, v2
	v_mov_b32_e32 v8, v2
	v_mov_b32_e32 v9, v2
	v_mov_b32_e32 v10, v2
	v_mov_b32_e32 v11, v2
	v_mov_b32_e32 v12, v2
	v_mov_b32_e32 v13, v2
	v_mov_b32_e32 v14, v2
	v_mov_b32_e32 v15, v2
	s_barrier
